# P4 epilogue stores made write-through (sc1) so the grid barrier's L2 write-back finds nothing dirty
# baseline (speedup 1.0000x reference)
.LBB0_1053:
	s_lshl_b32 s0, s50, 8
	s_add_i32 s0, s78, s0
	s_and_b32 s0, s0, 0x7fffff80
	s_lshl_b32 s0, s0, 1
	s_add_u32 s58, s79, s0
	s_addc_u32 s59, s82, 0
	s_lshl_b32 s0, s50, 2
	s_or_b32 s0, s0, s74
	s_mulk_i32 s0, 0x60
	s_ashr_i32 s1, s0, 31
	s_lshl_b64 s[0:1], s[0:1], 1
	s_add_u32 s54, s10, s0
	s_addc_u32 s55, s11, s1
	s_and_b64 s[0:1], s[8:9], exec
	s_cselect_b32 s0, s87, 0x340000
	s_add_u32 s50, s38, s0
	s_addc_u32 s51, s39, 0
	v_lshl_add_u64 v[4:5], v[200:201], 4, s[50:51]
	global_load_dwordx4 v[164:167], v[4:5], off
	global_load_dwordx4 v[236:239], v[4:5], off offset:2048
	global_load_dwordx4 v[240:243], v[4:5], off offset:2304
	global_load_dwordx4 v[244:247], v[4:5], off offset:2560
	global_load_dwordx4 v[248:251], v[4:5], off offset:2816
	v_add_u32_e32 v206, 16, v200
	v_add_u32_e32 v204, 32, v200
	v_add_u32_e32 v202, 48, v200
	v_ashrrev_i32_e32 v207, 31, v206
	v_ashrrev_i32_e32 v205, 31, v204
	v_ashrrev_i32_e32 v203, 31, v202
	v_lshl_add_u64 v[4:5], v[206:207], 4, s[50:51]
	v_lshl_add_u64 v[122:123], v[204:205], 4, s[50:51]
	v_lshl_add_u64 v[124:125], v[202:203], 4, s[50:51]
	global_load_dwordx4 v[178:181], v[4:5], off
	global_load_dwordx4 v[142:145], v[122:123], off
	s_nop 0
	global_load_dwordx4 v[122:125], v[124:125], off
	v_cndmask_b32_e64 v3, v218, v219, s[8:9]
	v_lshlrev_b64 v[210:211], 1, v[162:163]
	v_lshl_add_u64 v[198:199], v[8:9], 3, s[22:23]
	s_mov_b64 s[8:9], -1
	s_and_b64 vcc, exec, s[52:53]
	s_waitcnt vmcnt(0)
	v_mov_b32_e32 v4, v165
	v_mov_b32_e32 v5, v166
	v_mov_b32_e32 v165, v167
	v_pk_add_f32 v[4:5], v[4:5], v[164:165]
	s_nop 0
	v_add_f32_e32 v4, v4, v5
	v_fmaak_f32 v4, v3, v4, 0x358637bd
	v_rsq_f32_e32 v220, v4
	v_lshl_add_u64 v[4:5], s[58:59], 0, v[210:211]
	v_pk_mul_f32 v[160:161], v[160:161], v[220:221] op_sel_hi:[1,0]
	v_pk_mul_f32 v[208:209], v[158:159], v[220:221] op_sel_hi:[1,0]
	v_pk_mul_f32 v[156:157], v[156:157], v[220:221] op_sel_hi:[1,0]
	v_pk_mul_f32 v[158:159], v[154:155], v[220:221] op_sel_hi:[1,0]
	v_pk_mul_f32 v[152:153], v[152:153], v[220:221] op_sel_hi:[1,0]
	v_pk_mul_f32 v[154:155], v[150:151], v[220:221] op_sel_hi:[1,0]
	v_pk_mul_f32 v[148:149], v[148:149], v[220:221] op_sel_hi:[1,0]
	v_pk_mul_f32 v[150:151], v[146:147], v[220:221] op_sel_hi:[1,0]
	s_cbranch_vccz .LBB0_1063
	s_and_b64 vcc, exec, s[56:57]
	s_cbranch_vccz .LBB0_1060
	v_lshlrev_b64 v[146:147], 11, v[200:201]
	v_lshl_add_u64 v[146:147], v[4:5], 0, v[146:147]
	s_and_b64 vcc, exec, s[26:27]
	s_cbranch_vccz .LBB0_1057
	v_cvt_pk_bf16_f32 v162, v208, v209
	v_cvt_pk_bf16_f32 v163, v160, v161
	v_cvt_pk_bf16_f32 v164, v158, v159
	v_cvt_pk_bf16_f32 v165, v156, v157
	global_store_dwordx4 v[146:147], v[162:165], off sc1
	s_mov_b64 s[8:9], 0
	s_nop 0
	v_cvt_pk_bf16_f32 v162, v154, v155
	v_cvt_pk_bf16_f32 v163, v152, v153
	v_cvt_pk_bf16_f32 v164, v150, v151
	v_cvt_pk_bf16_f32 v165, v148, v149
	global_store_dwordx4 v[146:147], v[162:165], off offset:64 sc1
.LBB0_1057:
	s_andn2_b64 vcc, exec, s[8:9]
	s_cbranch_vccnz .LBB0_1059
	v_mul_f32_e32 v7, v209, v209
	v_mul_f32_e32 v162, v161, v161
	v_fmac_f32_e32 v7, v208, v208
	v_fmac_f32_e32 v162, v160, v160
	v_add_f32_e32 v7, v7, v162
	v_mul_f32_e32 v162, v159, v159
	v_mul_f32_e32 v163, v157, v157
	v_fmac_f32_e32 v162, v158, v158
	v_fmac_f32_e32 v163, v156, v156
	v_add_f32_e32 v162, v162, v163
	v_add_f32_e32 v7, v7, v162
	v_mul_f32_e32 v162, v155, v155
	v_mul_f32_e32 v163, v153, v153
	v_fmac_f32_e32 v162, v154, v154
	v_fmac_f32_e32 v163, v152, v152
	v_add_f32_e32 v162, v162, v163
	v_mul_f32_e32 v163, v151, v151
	v_mul_f32_e32 v164, v149, v149
	v_fmac_f32_e32 v163, v150, v150
	v_fmac_f32_e32 v164, v148, v148
	v_add_f32_e32 v163, v163, v164
	v_add_f32_e32 v162, v162, v163
	v_add_f32_e32 v7, v7, v162
	v_mov_b32_e32 v162, v7
	s_nop 1
	v_permlane16_swap_b32_e32 v7, v162
	v_add_f32_e32 v7, v7, v162
	v_mov_b32_e32 v162, v7
	s_nop 1
	v_permlane32_swap_b32_e32 v7, v162
	v_add_f32_e32 v7, v7, v162
	v_fmamk_f32 v7, v7, 0x3c800000, v217
	v_rsq_f32_e32 v7, v7
	v_pk_mul_f32 v[162:163], v[38:39], v[208:209]
	v_pk_mul_f32 v[164:165], v[40:41], v[160:161]
	v_pk_mul_f32 v[168:169], v[34:35], v[158:159]
	v_mul_f32_e32 v162, v162, v7
	v_mul_f32_e32 v163, v163, v7
	v_cvt_pk_bf16_f32 v162, v162, v163
	v_mul_f32_e32 v163, v164, v7
	v_mul_f32_e32 v164, v165, v7
	v_pk_mul_f32 v[166:167], v[36:37], v[156:157]
	v_cvt_pk_bf16_f32 v163, v163, v164
	v_mul_f32_e32 v164, v168, v7
	v_mul_f32_e32 v165, v169, v7
	v_cvt_pk_bf16_f32 v164, v164, v165
	v_mul_f32_e32 v165, v166, v7
	v_mul_f32_e32 v166, v167, v7
	v_cvt_pk_bf16_f32 v165, v165, v166
	global_store_dwordx4 v[146:147], v[162:165], off sc1
	v_pk_mul_f32 v[168:169], v[26:27], v[150:151]
	v_pk_mul_f32 v[166:167], v[28:29], v[148:149]
	v_pk_mul_f32 v[162:163], v[30:31], v[154:155]
	v_pk_mul_f32 v[164:165], v[32:33], v[152:153]
	v_mul_f32_e32 v162, v162, v7
	v_mul_f32_e32 v163, v163, v7
	v_cvt_pk_bf16_f32 v162, v162, v163
	v_mul_f32_e32 v163, v164, v7
	v_mul_f32_e32 v164, v165, v7
	v_cvt_pk_bf16_f32 v163, v163, v164
	v_mul_f32_e32 v164, v168, v7
	v_mul_f32_e32 v165, v169, v7
	v_cvt_pk_bf16_f32 v164, v164, v165
	v_mul_f32_e32 v165, v166, v7
	v_mul_f32_e32 v7, v167, v7
	v_cvt_pk_bf16_f32 v165, v165, v7
	global_store_dwordx4 v[146:147], v[162:165], off offset:64 sc1

.LBB0_1060:
	s_nop 0
	v_mov_b64_e32 v[162:163], v[174:175]
	v_mov_b64_e32 v[166:167], v[170:171]
	s_andn2_b64 vcc, exec, s[8:9]
	v_mov_b64_e32 v[164:165], v[176:177]
	v_mov_b64_e32 v[168:169], v[172:173]
	s_cbranch_vccnz .LBB0_1062
	v_ashrrev_i32_e32 v7, 31, v206
	v_lshrrev_b32_e32 v7, 19, v7
	v_add_u32_e32 v7, v206, v7
	v_and_b32_e32 v7, 0xffffe000, v7
	v_sub_u32_e32 v146, v206, v7
	v_ashrrev_i32_e32 v147, 31, v146
	v_lshlrev_b64 v[146:147], 7, v[146:147]
	v_lshl_add_u64 v[146:147], v[198:199], 0, v[146:147]
	global_load_dwordx4 v[166:169], v[146:147], off offset:16
	global_load_dwordx4 v[162:165], v[146:147], off
	v_mul_f32_e32 v7, v209, v209
	v_mul_f32_e32 v146, v161, v161
	v_fmac_f32_e32 v7, v208, v208
	v_fmac_f32_e32 v146, v160, v160
	v_add_f32_e32 v7, v7, v146
	v_mul_f32_e32 v146, v159, v159
	v_mul_f32_e32 v147, v157, v157
	v_fmac_f32_e32 v146, v158, v158
	v_fmac_f32_e32 v147, v156, v156
	v_add_f32_e32 v146, v146, v147
	v_add_f32_e32 v7, v7, v146
	v_mov_b32_e32 v146, v7
	s_nop 1
	v_permlane16_swap_b32_e32 v7, v146
	v_add_f32_e32 v7, v7, v146
	v_mov_b32_e32 v146, v7
	s_nop 1
	v_permlane32_swap_b32_e32 v7, v146
	v_add_f32_e32 v7, v7, v146
	v_fmamk_f32 v7, v7, 0x3d000000, v217
	v_rsq_f32_e32 v146, v7
	v_mov_b32_e32 v220, v208
	v_mov_b32_e32 v221, v158
	v_mov_b32_e32 v222, v38
	v_pk_mul_f32 v[220:221], v[220:221], v[146:147] op_sel_hi:[1,0]
	v_mov_b32_e32 v223, v34
	v_pk_mul_f32 v[220:221], v[222:223], v[220:221]
	s_nop 0
	v_pk_mul_f32 v[224:225], v[174:175], v[220:221]
	v_pk_mul_f32 v[220:221], v[174:175], v[220:221] op_sel:[1,0] op_sel_hi:[0,1]
	v_add_f32_e32 v147, v220, v221
	v_mov_b32_e32 v220, v209
	v_mov_b32_e32 v221, v159
	v_sub_f32_e32 v7, v224, v225
	v_pk_mul_f32 v[220:221], v[220:221], v[146:147] op_sel_hi:[1,0]
	v_mov_b32_e32 v224, v39
	v_mov_b32_e32 v225, v35
	v_pk_mul_f32 v[220:221], v[224:225], v[220:221]
	v_mul_f32_e32 v201, 0x3e16c740, v147
	v_pk_mul_f32 v[226:227], v[176:177], v[220:221]
	v_pk_mul_f32 v[220:221], v[176:177], v[220:221] op_sel:[1,0] op_sel_hi:[0,1]
	v_sub_f32_e32 v147, v226, v227
	v_mul_f32_e32 v230, 0x3e16c740, v147
	v_add_f32_e32 v147, v220, v221
	v_mov_b32_e32 v220, v160
	v_mov_b32_e32 v221, v156
	v_pk_mul_f32 v[220:221], v[220:221], v[146:147] op_sel_hi:[1,0]
	v_mov_b32_e32 v226, v40
	v_mov_b32_e32 v227, v36
	v_pk_mul_f32 v[220:221], v[226:227], v[220:221]
	v_mul_f32_e32 v231, 0x3e16c740, v147
	v_pk_mul_f32 v[228:229], v[170:171], v[220:221]
	v_pk_mul_f32 v[220:221], v[170:171], v[220:221] op_sel:[1,0] op_sel_hi:[0,1]
	v_sub_f32_e32 v147, v228, v229
	v_mul_f32_e32 v232, 0x3e16c740, v147
	v_add_f32_e32 v147, v220, v221
	v_mov_b32_e32 v220, v161
	v_mov_b32_e32 v221, v157
	v_mul_f32_e32 v233, 0x3e16c740, v147
	v_pk_mul_f32 v[146:147], v[220:221], v[146:147] op_sel_hi:[1,0]
	v_mov_b32_e32 v220, v41
	v_mov_b32_e32 v221, v37
	v_pk_mul_f32 v[146:147], v[220:221], v[146:147]
	v_mul_f32_e32 v7, 0x3e16c740, v7
	v_pk_mul_f32 v[228:229], v[172:173], v[146:147]
	v_pk_mul_f32 v[146:147], v[172:173], v[146:147] op_sel:[1,0] op_sel_hi:[0,1]
	v_add_f32_e32 v146, v146, v147
	v_mul_f32_e32 v234, 0x3e16c740, v146
	v_mov_b64_e32 v[146:147], s[28:29]
	v_sub_f32_e32 v228, v228, v229
	v_mad_i64_i32 v[146:147], s[0:1], v200, s70, v[146:147]
	v_mul_f32_e32 v229, 0x3e16c740, v228
	v_cvt_pk_bf16_f32 v228, v7, v230
	v_lshl_add_u64 v[146:147], v[8:9], 1, v[146:147]
	v_cvt_pk_bf16_f32 v229, v232, v229
	global_store_dwordx2 v[146:147], v[228:229], off offset:128 sc1
	v_cvt_pk_bf16_f32 v228, v201, v231
	v_mul_f32_e32 v7, v155, v155
	v_mul_f32_e32 v201, v153, v153
	v_fmac_f32_e32 v7, v154, v154
	v_fmac_f32_e32 v201, v152, v152
	v_add_f32_e32 v7, v7, v201
	v_mul_f32_e32 v201, v151, v151
	v_mul_f32_e32 v230, v149, v149
	v_fmac_f32_e32 v201, v150, v150
	v_fmac_f32_e32 v230, v148, v148
	v_add_f32_e32 v201, v201, v230
	v_add_f32_e32 v7, v7, v201
	v_mov_b32_e32 v201, v7
	s_nop 1
	v_permlane16_swap_b32_e32 v7, v201
	v_add_f32_e32 v7, v7, v201
	v_mov_b32_e32 v201, v7
	s_nop 1
	v_permlane32_swap_b32_e32 v7, v201
	v_add_f32_e32 v7, v7, v201
	v_fmamk_f32 v7, v7, 0x3d000000, v217
	v_rsq_f32_e32 v230, v7
	v_cvt_pk_bf16_f32 v229, v233, v234
	global_store_dwordx2 v[146:147], v[228:229], off offset:160 sc1
	v_mov_b32_e32 v228, v154
	v_mov_b32_e32 v229, v150
	v_pk_mul_f32 v[228:229], v[228:229], v[230:231] op_sel_hi:[1,0]
	s_nop 0
	v_pk_mul_f32 v[222:223], v[222:223], v[228:229]
	s_nop 0
	v_pk_mul_f32 v[228:229], v[174:175], v[222:223]
	v_pk_mul_f32 v[222:223], v[174:175], v[222:223] op_sel:[1,0] op_sel_hi:[0,1]
	v_add_f32_e32 v201, v222, v223
	v_mov_b32_e32 v222, v155
	v_mov_b32_e32 v223, v151
	v_pk_mul_f32 v[222:223], v[222:223], v[230:231] op_sel_hi:[1,0]
	v_sub_f32_e32 v7, v228, v229
	v_pk_mul_f32 v[222:223], v[224:225], v[222:223]
	v_mul_f32_e32 v7, 0x3e16c740, v7
	v_pk_mul_f32 v[224:225], v[176:177], v[222:223]
	v_pk_mul_f32 v[222:223], v[176:177], v[222:223] op_sel:[1,0] op_sel_hi:[0,1]
	v_add_f32_e32 v222, v222, v223
	v_mul_f32_e32 v229, 0x3e16c740, v222
	v_mov_b32_e32 v222, v152
	v_mov_b32_e32 v223, v148
	v_pk_mul_f32 v[222:223], v[222:223], v[230:231] op_sel_hi:[1,0]
	v_sub_f32_e32 v224, v224, v225
	v_pk_mul_f32 v[222:223], v[226:227], v[222:223]
	v_mul_f32_e32 v228, 0x3e16c740, v224
	v_pk_mul_f32 v[224:225], v[170:171], v[222:223]
	v_pk_mul_f32 v[222:223], v[170:171], v[222:223] op_sel:[1,0] op_sel_hi:[0,1]
	v_add_f32_e32 v222, v222, v223
	v_sub_f32_e32 v224, v224, v225
	v_mul_f32_e32 v225, 0x3e16c740, v222
	v_mov_b32_e32 v222, v153
	v_mov_b32_e32 v223, v149
	v_pk_mul_f32 v[222:223], v[222:223], v[230:231] op_sel_hi:[1,0]
	v_mul_f32_e32 v224, 0x3e16c740, v224
	v_pk_mul_f32 v[220:221], v[220:221], v[222:223]
	v_mul_f32_e32 v201, 0x3e16c740, v201
	v_pk_mul_f32 v[222:223], v[172:173], v[220:221]
	v_pk_mul_f32 v[220:221], v[172:173], v[220:221] op_sel:[1,0] op_sel_hi:[0,1]
	v_sub_f32_e32 v222, v222, v223
	v_add_f32_e32 v220, v220, v221
	v_mul_f32_e32 v222, 0x3e16c740, v222
	v_mul_f32_e32 v223, 0x3e16c740, v220
	v_cvt_pk_bf16_f32 v220, v7, v228
	v_cvt_pk_bf16_f32 v221, v224, v222
	global_store_dwordx2 v[146:147], v[220:221], off offset:320 sc1
	v_cvt_pk_bf16_f32 v220, v201, v229
	v_cvt_pk_bf16_f32 v221, v225, v223
	global_store_dwordx2 v[146:147], v[220:221], off offset:352 sc1

.Lew4_0:
	v_mul_f32_e32 v162, v161, v161
	v_fmac_f32_e32 v7, v208, v208
	v_fmac_f32_e32 v162, v160, v160
	v_add_f32_e32 v7, v7, v162
	v_mul_f32_e32 v162, v159, v159
	v_mul_f32_e32 v163, v157, v157
	v_fmac_f32_e32 v162, v158, v158
	v_fmac_f32_e32 v163, v156, v156
	v_add_f32_e32 v162, v162, v163
	v_add_f32_e32 v7, v7, v162
	v_mul_f32_e32 v162, v155, v155
	v_mul_f32_e32 v163, v153, v153
	v_fmac_f32_e32 v162, v154, v154
	v_fmac_f32_e32 v163, v152, v152
	v_add_f32_e32 v162, v162, v163
	v_mul_f32_e32 v163, v151, v151
	v_mul_f32_e32 v164, v149, v149
	v_fmac_f32_e32 v163, v150, v150
	v_fmac_f32_e32 v164, v148, v148
	v_add_f32_e32 v163, v163, v164
	v_add_f32_e32 v162, v162, v163
	v_add_f32_e32 v7, v7, v162
	v_mov_b32_e32 v162, v7
	s_nop 1
	v_permlane16_swap_b32_e32 v7, v162
	v_add_f32_e32 v7, v7, v162
	v_mov_b32_e32 v162, v7
	s_nop 1
	v_permlane32_swap_b32_e32 v7, v162
	v_add_f32_e32 v7, v7, v162
	v_fmamk_f32 v7, v7, 0x3c800000, v217
	v_rsq_f32_e32 v7, v7
	v_pk_mul_f32 v[164:165], v[38:39], v[208:209]
	v_pk_mul_f32 v[160:161], v[40:41], v[160:161]
	v_pk_mul_f32 v[166:167], v[36:37], v[156:157]
	v_mul_f32_e32 v7, 0x3e16c740, v7
	v_pk_mul_f32 v[158:159], v[34:35], v[158:159]
	v_mul_f32_e32 v156, v164, v7
	v_mul_f32_e32 v157, v165, v7
	v_cvt_pk_bf16_f32 v156, v156, v157
	v_mul_f32_e32 v157, v160, v7
	v_mul_f32_e32 v158, v158, v7
	v_mul_f32_e32 v159, v159, v7
	v_mad_i64_i32 v[162:163], s[0:1], v200, s70, v[146:147]
	v_mul_f32_e32 v160, v161, v7
	v_cvt_pk_bf16_f32 v157, v157, v160
	v_cvt_pk_bf16_f32 v158, v158, v159
	v_mul_f32_e32 v159, v166, v7
	v_pk_mul_f32 v[154:155], v[30:31], v[154:155]
	v_mul_f32_e32 v160, v167, v7
	v_cvt_pk_bf16_f32 v159, v159, v160
	global_store_dwordx4 v[162:163], v[156:159], off sc1
	v_pk_mul_f32 v[152:153], v[32:33], v[152:153]
	v_pk_mul_f32 v[150:151], v[26:27], v[150:151]
	v_pk_mul_f32 v[156:157], v[28:29], v[148:149]
	v_mul_f32_e32 v148, v154, v7
	v_mul_f32_e32 v149, v155, v7
	v_cvt_pk_bf16_f32 v148, v148, v149
	v_mul_f32_e32 v149, v152, v7
	v_mul_f32_e32 v150, v150, v7
	v_mul_f32_e32 v151, v151, v7
	v_mul_f32_e32 v152, v153, v7
	v_cvt_pk_bf16_f32 v149, v149, v152
	v_cvt_pk_bf16_f32 v150, v150, v151
	v_mul_f32_e32 v151, v156, v7
	v_mul_f32_e32 v7, v157, v7
	v_cvt_pk_bf16_f32 v151, v151, v7
	global_store_dwordx4 v[162:163], v[148:151], off offset:64 sc1
	v_mov_b64_e32 v[166:167], v[170:171]
	v_mov_b64_e32 v[162:163], v[174:175]
	v_mov_b64_e32 v[168:169], v[172:173]
	v_mov_b64_e32 v[164:165], v[176:177]
.LBB0_1065:
	v_add_f32_e32 v7, v178, v179
	v_add_f32_e32 v148, v180, v181
	v_add_f32_e32 v7, v7, v148
	v_fmaak_f32 v7, v3, v7, 0x358637bd
	v_rsq_f32_e32 v156, v7
	v_cndmask_b32_e64 v7, 0, 1, s[52:53]
	v_cmp_ne_u32_e64 s[8:9], 1, v7
	s_andn2_b64 vcc, exec, s[52:53]
	v_pk_mul_f32 v[150:151], v[140:141], v[156:157] op_sel_hi:[1,0]
	v_pk_mul_f32 v[154:155], v[138:139], v[156:157] op_sel_hi:[1,0]
	v_pk_mul_f32 v[148:149], v[136:137], v[156:157] op_sel_hi:[1,0]
	v_pk_mul_f32 v[152:153], v[134:135], v[156:157] op_sel_hi:[1,0]
	v_pk_mul_f32 v[136:137], v[132:133], v[156:157] op_sel_hi:[1,0]
	v_pk_mul_f32 v[140:141], v[130:131], v[156:157] op_sel_hi:[1,0]
	v_pk_mul_f32 v[134:135], v[128:129], v[156:157] op_sel_hi:[1,0]
	v_pk_mul_f32 v[138:139], v[126:127], v[156:157] op_sel_hi:[1,0]
	s_mov_b64 s[52:53], -1
	s_cbranch_vccnz .LBB0_1075
	s_and_b64 vcc, exec, s[6:7]
	s_cbranch_vccnz .LBB0_1072
	v_lshlrev_b64 v[126:127], 11, v[206:207]
	v_lshl_add_u64 v[126:127], v[4:5], 0, v[126:127]
	s_andn2_b64 vcc, exec, s[26:27]
	s_cbranch_vccnz .LBB0_1069
	v_cvt_pk_bf16_f32 v128, v154, v155
	v_cvt_pk_bf16_f32 v129, v150, v151
	v_cvt_pk_bf16_f32 v130, v152, v153
	v_cvt_pk_bf16_f32 v131, v148, v149
	s_mov_b64 s[52:53], 0
	global_store_dwordx4 v[126:127], v[128:131], off sc1
	s_nop 1
	v_cvt_pk_bf16_f32 v128, v140, v141
	v_cvt_pk_bf16_f32 v129, v136, v137
	v_cvt_pk_bf16_f32 v130, v138, v139
	v_cvt_pk_bf16_f32 v131, v134, v135
	global_store_dwordx4 v[126:127], v[128:131], off offset:64 sc1
.LBB0_1069:
	s_andn2_b64 vcc, exec, s[52:53]
	s_cbranch_vccnz .LBB0_1071
	v_mul_f32_e32 v7, v155, v155
	v_mul_f32_e32 v128, v151, v151
	v_fmac_f32_e32 v7, v154, v154
	v_fmac_f32_e32 v128, v150, v150
	v_add_f32_e32 v7, v7, v128
	v_mul_f32_e32 v128, v153, v153
	v_mul_f32_e32 v129, v149, v149
	v_fmac_f32_e32 v128, v152, v152
	v_fmac_f32_e32 v129, v148, v148
	v_add_f32_e32 v128, v128, v129
	v_add_f32_e32 v7, v7, v128
	v_mul_f32_e32 v128, v141, v141
	v_mul_f32_e32 v129, v137, v137
	v_fmac_f32_e32 v128, v140, v140
	v_fmac_f32_e32 v129, v136, v136
	v_add_f32_e32 v128, v128, v129
	v_mul_f32_e32 v129, v139, v139
	v_mul_f32_e32 v130, v135, v135
	v_fmac_f32_e32 v129, v138, v138
	v_fmac_f32_e32 v130, v134, v134
	v_add_f32_e32 v129, v129, v130
	v_add_f32_e32 v128, v128, v129
	v_add_f32_e32 v7, v7, v128
	v_mov_b32_e32 v128, v7
	s_nop 1
	v_permlane16_swap_b32_e32 v7, v128
	v_add_f32_e32 v7, v7, v128
	v_mov_b32_e32 v128, v7
	s_nop 1
	v_permlane32_swap_b32_e32 v7, v128
	v_add_f32_e32 v7, v7, v128
	v_fmamk_f32 v7, v7, 0x3c800000, v217
	v_rsq_f32_e32 v7, v7
	v_pk_mul_f32 v[128:129], v[38:39], v[154:155]
	v_pk_mul_f32 v[130:131], v[40:41], v[150:151]
	v_pk_mul_f32 v[156:157], v[34:35], v[152:153]
	v_mul_f32_e32 v128, v128, v7
	v_mul_f32_e32 v129, v129, v7
	v_cvt_pk_bf16_f32 v128, v128, v129
	v_mul_f32_e32 v129, v130, v7
	v_mul_f32_e32 v130, v131, v7
	v_pk_mul_f32 v[132:133], v[36:37], v[148:149]
	v_cvt_pk_bf16_f32 v129, v129, v130
	v_mul_f32_e32 v130, v156, v7
	v_mul_f32_e32 v131, v157, v7
	v_cvt_pk_bf16_f32 v130, v130, v131
	v_mul_f32_e32 v131, v132, v7
	v_mul_f32_e32 v132, v133, v7
	v_cvt_pk_bf16_f32 v131, v131, v132
	global_store_dwordx4 v[126:127], v[128:131], off sc1
	v_pk_mul_f32 v[156:157], v[26:27], v[138:139]
	v_pk_mul_f32 v[132:133], v[28:29], v[134:135]
	v_pk_mul_f32 v[128:129], v[30:31], v[140:141]
	v_pk_mul_f32 v[130:131], v[32:33], v[136:137]
	v_mul_f32_e32 v128, v128, v7
	v_mul_f32_e32 v129, v129, v7
	v_cvt_pk_bf16_f32 v128, v128, v129
	v_mul_f32_e32 v129, v130, v7
	v_mul_f32_e32 v130, v131, v7
	v_cvt_pk_bf16_f32 v129, v129, v130
	v_mul_f32_e32 v130, v156, v7
	v_mul_f32_e32 v131, v157, v7
	v_cvt_pk_bf16_f32 v130, v130, v131
	v_mul_f32_e32 v131, v132, v7
	v_mul_f32_e32 v7, v133, v7
	v_cvt_pk_bf16_f32 v131, v131, v7
	global_store_dwordx4 v[126:127], v[128:131], off offset:64 sc1

.Lew4_1:
	v_mov_b64_e32 v[126:127], v[162:163]
	v_mov_b64_e32 v[130:131], v[166:167]
	s_andn2_b64 vcc, exec, s[52:53]
	v_mov_b64_e32 v[128:129], v[164:165]
	v_mov_b64_e32 v[132:133], v[168:169]
	s_cbranch_vccnz .LBB0_1074
	v_ashrrev_i32_e32 v7, 31, v204
	v_lshrrev_b32_e32 v7, 19, v7
	v_add_u32_e32 v7, v204, v7
	v_and_b32_e32 v7, 0xffffe000, v7
	v_sub_u32_e32 v126, v204, v7
	v_ashrrev_i32_e32 v127, 31, v126
	v_lshlrev_b64 v[126:127], 7, v[126:127]
	v_lshl_add_u64 v[126:127], v[198:199], 0, v[126:127]
	global_load_dwordx4 v[130:133], v[126:127], off offset:16
	s_nop 0
	global_load_dwordx4 v[126:129], v[126:127], off
	v_mul_f32_e32 v7, v155, v155
	v_mul_f32_e32 v156, v151, v151
	v_fmac_f32_e32 v7, v154, v154
	v_fmac_f32_e32 v156, v150, v150
	v_add_f32_e32 v7, v7, v156
	v_mul_f32_e32 v156, v153, v153
	v_mul_f32_e32 v157, v149, v149
	v_fmac_f32_e32 v156, v152, v152
	v_fmac_f32_e32 v157, v148, v148
	v_add_f32_e32 v156, v156, v157
	v_add_f32_e32 v7, v7, v156
	v_mov_b32_e32 v156, v7
	s_nop 1
	v_permlane16_swap_b32_e32 v7, v156
	v_add_f32_e32 v7, v7, v156
	v_mov_b32_e32 v156, v7
	s_nop 1
	v_permlane32_swap_b32_e32 v7, v156
	v_add_f32_e32 v7, v7, v156
	v_fmamk_f32 v7, v7, 0x3d000000, v217
	v_rsq_f32_e32 v156, v7
	v_mov_b32_e32 v158, v154
	v_mov_b32_e32 v159, v152
	v_mov_b32_e32 v160, v38
	v_pk_mul_f32 v[158:159], v[158:159], v[156:157] op_sel_hi:[1,0]
	v_mov_b32_e32 v161, v34
	v_pk_mul_f32 v[158:159], v[160:161], v[158:159]
	s_nop 0
	v_pk_mul_f32 v[170:171], v[162:163], v[158:159]
	v_pk_mul_f32 v[158:159], v[162:163], v[158:159] op_sel:[1,0] op_sel_hi:[0,1]
	v_add_f32_e32 v157, v158, v159
	v_mov_b32_e32 v158, v155
	v_mov_b32_e32 v159, v153
	v_sub_f32_e32 v7, v170, v171
	v_pk_mul_f32 v[158:159], v[158:159], v[156:157] op_sel_hi:[1,0]
	v_mov_b32_e32 v170, v39
	v_mov_b32_e32 v171, v35
	v_pk_mul_f32 v[158:159], v[170:171], v[158:159]
	v_mul_f32_e32 v176, 0x3e16c740, v157
	v_pk_mul_f32 v[172:173], v[164:165], v[158:159]
	v_pk_mul_f32 v[158:159], v[164:165], v[158:159] op_sel:[1,0] op_sel_hi:[0,1]
	v_sub_f32_e32 v157, v172, v173
	v_mul_f32_e32 v177, 0x3e16c740, v157
	v_add_f32_e32 v157, v158, v159
	v_mov_b32_e32 v158, v150
	v_mov_b32_e32 v159, v148
	v_pk_mul_f32 v[158:159], v[158:159], v[156:157] op_sel_hi:[1,0]
	v_mov_b32_e32 v172, v40
	v_mov_b32_e32 v173, v36
	v_pk_mul_f32 v[158:159], v[172:173], v[158:159]
	v_mul_f32_e32 v178, 0x3e16c740, v157
	v_pk_mul_f32 v[174:175], v[166:167], v[158:159]
	v_pk_mul_f32 v[158:159], v[166:167], v[158:159] op_sel:[1,0] op_sel_hi:[0,1]
	v_sub_f32_e32 v157, v174, v175
	v_mul_f32_e32 v179, 0x3e16c740, v157
	v_add_f32_e32 v157, v158, v159
	v_mov_b32_e32 v158, v151
	v_mov_b32_e32 v159, v149
	v_mul_f32_e32 v180, 0x3e16c740, v157
	v_pk_mul_f32 v[156:157], v[158:159], v[156:157] op_sel_hi:[1,0]
	v_mov_b32_e32 v158, v41
	v_mov_b32_e32 v159, v37
	v_pk_mul_f32 v[156:157], v[158:159], v[156:157]
	v_mul_f32_e32 v7, 0x3e16c740, v7
	v_pk_mul_f32 v[174:175], v[168:169], v[156:157]
	v_pk_mul_f32 v[156:157], v[168:169], v[156:157] op_sel:[1,0] op_sel_hi:[0,1]
	v_add_f32_e32 v156, v156, v157
	v_mul_f32_e32 v181, 0x3e16c740, v156
	v_mov_b64_e32 v[156:157], s[28:29]
	v_sub_f32_e32 v174, v174, v175
	v_mad_i64_i32 v[156:157], s[0:1], v206, s70, v[156:157]
	v_mul_f32_e32 v175, 0x3e16c740, v174
	v_cvt_pk_bf16_f32 v174, v7, v177
	v_lshl_add_u64 v[156:157], v[8:9], 1, v[156:157]
	v_cvt_pk_bf16_f32 v175, v179, v175
	global_store_dwordx2 v[156:157], v[174:175], off offset:128 sc1
	v_cvt_pk_bf16_f32 v174, v176, v178
	v_mul_f32_e32 v7, v141, v141
	v_mul_f32_e32 v176, v137, v137
	v_fmac_f32_e32 v7, v140, v140
	v_fmac_f32_e32 v176, v136, v136
	v_add_f32_e32 v7, v7, v176
	v_mul_f32_e32 v176, v139, v139
	v_mul_f32_e32 v177, v135, v135
	v_fmac_f32_e32 v176, v138, v138
	v_fmac_f32_e32 v177, v134, v134
	v_add_f32_e32 v176, v176, v177
	v_add_f32_e32 v7, v7, v176
	v_mov_b32_e32 v176, v7
	s_nop 1
	v_permlane16_swap_b32_e32 v7, v176
	v_add_f32_e32 v7, v7, v176
	v_mov_b32_e32 v176, v7
	s_nop 1
	v_permlane32_swap_b32_e32 v7, v176
	v_add_f32_e32 v7, v7, v176
	v_fmamk_f32 v7, v7, 0x3d000000, v217
	v_rsq_f32_e32 v176, v7
	v_cvt_pk_bf16_f32 v175, v180, v181
	global_store_dwordx2 v[156:157], v[174:175], off offset:160 sc1
	v_mov_b32_e32 v174, v140
	v_mov_b32_e32 v175, v138
	v_pk_mul_f32 v[174:175], v[174:175], v[176:177] op_sel_hi:[1,0]
	s_nop 0
	v_pk_mul_f32 v[160:161], v[160:161], v[174:175]
	s_nop 0
	v_pk_mul_f32 v[174:175], v[162:163], v[160:161]
	v_pk_mul_f32 v[160:161], v[162:163], v[160:161] op_sel:[1,0] op_sel_hi:[0,1]
	v_add_f32_e32 v160, v160, v161
	v_sub_f32_e32 v7, v174, v175
	v_mul_f32_e32 v174, 0x3e16c740, v160
	v_mov_b32_e32 v160, v141
	v_mov_b32_e32 v161, v139
	v_pk_mul_f32 v[160:161], v[160:161], v[176:177] op_sel_hi:[1,0]
	v_mul_f32_e32 v7, 0x3e16c740, v7
	v_pk_mul_f32 v[160:161], v[170:171], v[160:161]
	s_nop 0
	v_pk_mul_f32 v[170:171], v[164:165], v[160:161]
	v_pk_mul_f32 v[160:161], v[164:165], v[160:161] op_sel:[1,0] op_sel_hi:[0,1]
	v_add_f32_e32 v160, v160, v161
	v_mul_f32_e32 v177, 0x3e16c740, v160
	v_mov_b32_e32 v160, v136
	v_mov_b32_e32 v161, v134
	v_pk_mul_f32 v[160:161], v[160:161], v[176:177] op_sel_hi:[1,0]
	v_sub_f32_e32 v170, v170, v171
	v_pk_mul_f32 v[160:161], v[172:173], v[160:161]
	v_mul_f32_e32 v175, 0x3e16c740, v170
	v_pk_mul_f32 v[170:171], v[166:167], v[160:161]
	v_pk_mul_f32 v[160:161], v[166:167], v[160:161] op_sel:[1,0] op_sel_hi:[0,1]
	v_add_f32_e32 v160, v160, v161
	v_sub_f32_e32 v170, v170, v171
	v_mul_f32_e32 v171, 0x3e16c740, v160
	v_mov_b32_e32 v160, v137
	v_mov_b32_e32 v161, v135
	v_pk_mul_f32 v[160:161], v[160:161], v[176:177] op_sel_hi:[1,0]
	v_mul_f32_e32 v170, 0x3e16c740, v170
	v_pk_mul_f32 v[158:159], v[158:159], v[160:161]
	s_nop 0
	v_pk_mul_f32 v[160:161], v[168:169], v[158:159]
	v_pk_mul_f32 v[158:159], v[168:169], v[158:159] op_sel:[1,0] op_sel_hi:[0,1]
	v_sub_f32_e32 v160, v160, v161
	v_add_f32_e32 v158, v158, v159
	v_mul_f32_e32 v160, 0x3e16c740, v160
	v_mul_f32_e32 v161, 0x3e16c740, v158
	v_cvt_pk_bf16_f32 v158, v7, v175
	v_cvt_pk_bf16_f32 v159, v170, v160
	global_store_dwordx2 v[156:157], v[158:159], off offset:320 sc1
	v_cvt_pk_bf16_f32 v158, v174, v177
	v_cvt_pk_bf16_f32 v159, v171, v161
	global_store_dwordx2 v[156:157], v[158:159], off offset:352 sc1

.Lew4_2:
	v_mul_f32_e32 v126, v151, v151
	v_fmac_f32_e32 v7, v154, v154
	v_fmac_f32_e32 v126, v150, v150
	v_add_f32_e32 v7, v7, v126
	v_mul_f32_e32 v126, v153, v153
	v_mul_f32_e32 v127, v149, v149
	v_fmac_f32_e32 v126, v152, v152
	v_fmac_f32_e32 v127, v148, v148
	v_add_f32_e32 v126, v126, v127
	v_add_f32_e32 v7, v7, v126
	v_mul_f32_e32 v126, v141, v141
	v_mul_f32_e32 v127, v137, v137
	v_fmac_f32_e32 v126, v140, v140
	v_fmac_f32_e32 v127, v136, v136
	v_add_f32_e32 v126, v126, v127
	v_mul_f32_e32 v127, v139, v139
	v_mul_f32_e32 v128, v135, v135
	v_fmac_f32_e32 v127, v138, v138
	v_fmac_f32_e32 v128, v134, v134
	v_add_f32_e32 v127, v127, v128
	v_add_f32_e32 v126, v126, v127
	v_add_f32_e32 v7, v7, v126
	v_mov_b32_e32 v126, v7
	s_nop 1
	v_permlane16_swap_b32_e32 v7, v126
	v_add_f32_e32 v7, v7, v126
	v_mov_b32_e32 v126, v7
	s_nop 1
	v_permlane32_swap_b32_e32 v7, v126
	v_add_f32_e32 v7, v7, v126
	v_fmamk_f32 v7, v7, 0x3c800000, v217
	v_rsq_f32_e32 v7, v7
	v_pk_mul_f32 v[126:127], v[38:39], v[154:155]
	v_pk_mul_f32 v[128:129], v[40:41], v[150:151]
	v_pk_mul_f32 v[132:133], v[36:37], v[148:149]
	v_mul_f32_e32 v7, 0x3e16c740, v7
	v_mul_f32_e32 v126, v126, v7
	v_mul_f32_e32 v127, v127, v7
	v_pk_mul_f32 v[148:149], v[34:35], v[152:153]
	v_cvt_pk_bf16_f32 v126, v126, v127
	v_mul_f32_e32 v127, v128, v7
	v_mul_f32_e32 v128, v129, v7
	v_cvt_pk_bf16_f32 v127, v127, v128
	v_mul_f32_e32 v128, v148, v7
	v_mul_f32_e32 v129, v149, v7
	v_mad_i64_i32 v[130:131], s[0:1], v206, s70, v[146:147]
	v_cvt_pk_bf16_f32 v128, v128, v129
	v_mul_f32_e32 v129, v132, v7
	v_mul_f32_e32 v132, v133, v7
	v_cvt_pk_bf16_f32 v129, v129, v132
	global_store_dwordx4 v[130:131], v[126:129], off sc1
	v_pk_mul_f32 v[132:133], v[28:29], v[134:135]
	v_pk_mul_f32 v[134:135], v[26:27], v[138:139]
	v_pk_mul_f32 v[126:127], v[30:31], v[140:141]
	v_pk_mul_f32 v[128:129], v[32:33], v[136:137]
	v_mul_f32_e32 v126, v126, v7
	v_mul_f32_e32 v127, v127, v7
	v_cvt_pk_bf16_f32 v126, v126, v127
	v_mul_f32_e32 v127, v128, v7
	v_mul_f32_e32 v128, v129, v7
	v_cvt_pk_bf16_f32 v127, v127, v128
	v_mul_f32_e32 v128, v134, v7
	v_mul_f32_e32 v129, v135, v7
	v_cvt_pk_bf16_f32 v128, v128, v129
	v_mul_f32_e32 v129, v132, v7
	v_mul_f32_e32 v7, v133, v7
	v_cvt_pk_bf16_f32 v129, v129, v7
	global_store_dwordx4 v[130:131], v[126:129], off offset:64 sc1
	v_mov_b64_e32 v[130:131], v[166:167]
	v_mov_b64_e32 v[132:133], v[168:169]
	v_mov_b64_e32 v[126:127], v[162:163]
	v_mov_b64_e32 v[128:129], v[164:165]
.LBB0_1077:
	v_add_f32_e32 v7, v142, v143
	v_add_f32_e32 v134, v144, v145
	v_add_f32_e32 v7, v7, v134
	v_fmaak_f32 v7, v3, v7, 0x358637bd
	v_rsq_f32_e32 v142, v7
	s_and_b64 vcc, exec, s[8:9]
	s_mov_b64 s[52:53], -1
	v_pk_mul_f32 v[136:137], v[120:121], v[142:143] op_sel_hi:[1,0]
	v_pk_mul_f32 v[140:141], v[118:119], v[142:143] op_sel_hi:[1,0]
	v_pk_mul_f32 v[134:135], v[116:117], v[142:143] op_sel_hi:[1,0]
	v_pk_mul_f32 v[138:139], v[114:115], v[142:143] op_sel_hi:[1,0]
	v_pk_mul_f32 v[116:117], v[112:113], v[142:143] op_sel_hi:[1,0]
	v_pk_mul_f32 v[120:121], v[110:111], v[142:143] op_sel_hi:[1,0]
	v_pk_mul_f32 v[114:115], v[108:109], v[142:143] op_sel_hi:[1,0]
	v_pk_mul_f32 v[118:119], v[106:107], v[142:143] op_sel_hi:[1,0]
	s_cbranch_vccnz .LBB0_1087
	s_and_b64 vcc, exec, s[6:7]
	s_cbranch_vccnz .LBB0_1084
	v_lshlrev_b64 v[106:107], 11, v[204:205]
	v_lshl_add_u64 v[106:107], v[4:5], 0, v[106:107]
	s_andn2_b64 vcc, exec, s[26:27]
	s_cbranch_vccnz .LBB0_1081
	v_cvt_pk_bf16_f32 v108, v140, v141
	v_cvt_pk_bf16_f32 v109, v136, v137
	v_cvt_pk_bf16_f32 v110, v138, v139
	v_cvt_pk_bf16_f32 v111, v134, v135
	s_mov_b64 s[52:53], 0
	global_store_dwordx4 v[106:107], v[108:111], off sc1
	s_nop 1
	v_cvt_pk_bf16_f32 v108, v120, v121
	v_cvt_pk_bf16_f32 v109, v116, v117
	v_cvt_pk_bf16_f32 v110, v118, v119
	v_cvt_pk_bf16_f32 v111, v114, v115
	global_store_dwordx4 v[106:107], v[108:111], off offset:64 sc1
.LBB0_1081:
	s_andn2_b64 vcc, exec, s[52:53]
	s_cbranch_vccnz .LBB0_1083
	v_mul_f32_e32 v7, v141, v141
	v_mul_f32_e32 v108, v137, v137
	v_fmac_f32_e32 v7, v140, v140
	v_fmac_f32_e32 v108, v136, v136
	v_add_f32_e32 v7, v7, v108
	v_mul_f32_e32 v108, v139, v139
	v_mul_f32_e32 v109, v135, v135
	v_fmac_f32_e32 v108, v138, v138
	v_fmac_f32_e32 v109, v134, v134
	v_add_f32_e32 v108, v108, v109
	v_add_f32_e32 v7, v7, v108
	v_mul_f32_e32 v108, v121, v121
	v_mul_f32_e32 v109, v117, v117
	v_fmac_f32_e32 v108, v120, v120
	v_fmac_f32_e32 v109, v116, v116
	v_add_f32_e32 v108, v108, v109
	v_mul_f32_e32 v109, v119, v119
	v_mul_f32_e32 v110, v115, v115
	v_fmac_f32_e32 v109, v118, v118
	v_fmac_f32_e32 v110, v114, v114
	v_add_f32_e32 v109, v109, v110
	v_add_f32_e32 v108, v108, v109
	v_add_f32_e32 v7, v7, v108
	v_mov_b32_e32 v108, v7
	s_nop 1
	v_permlane16_swap_b32_e32 v7, v108
	v_add_f32_e32 v7, v7, v108
	v_mov_b32_e32 v108, v7
	s_nop 1
	v_permlane32_swap_b32_e32 v7, v108
	v_add_f32_e32 v7, v7, v108
	v_fmamk_f32 v7, v7, 0x3c800000, v217
	v_rsq_f32_e32 v7, v7
	v_pk_mul_f32 v[108:109], v[38:39], v[140:141]
	v_pk_mul_f32 v[110:111], v[40:41], v[136:137]
	v_pk_mul_f32 v[142:143], v[34:35], v[138:139]
	v_mul_f32_e32 v108, v108, v7
	v_mul_f32_e32 v109, v109, v7
	v_cvt_pk_bf16_f32 v108, v108, v109
	v_mul_f32_e32 v109, v110, v7
	v_mul_f32_e32 v110, v111, v7
	v_pk_mul_f32 v[112:113], v[36:37], v[134:135]
	v_cvt_pk_bf16_f32 v109, v109, v110
	v_mul_f32_e32 v110, v142, v7
	v_mul_f32_e32 v111, v143, v7
	v_cvt_pk_bf16_f32 v110, v110, v111
	v_mul_f32_e32 v111, v112, v7
	v_mul_f32_e32 v112, v113, v7
	v_cvt_pk_bf16_f32 v111, v111, v112
	global_store_dwordx4 v[106:107], v[108:111], off sc1
	v_pk_mul_f32 v[142:143], v[26:27], v[118:119]
	v_pk_mul_f32 v[112:113], v[28:29], v[114:115]
	v_pk_mul_f32 v[108:109], v[30:31], v[120:121]
	v_pk_mul_f32 v[110:111], v[32:33], v[116:117]
	v_mul_f32_e32 v108, v108, v7
	v_mul_f32_e32 v109, v109, v7
	v_cvt_pk_bf16_f32 v108, v108, v109
	v_mul_f32_e32 v109, v110, v7
	v_mul_f32_e32 v110, v111, v7
	v_cvt_pk_bf16_f32 v109, v109, v110
	v_mul_f32_e32 v110, v142, v7
	v_mul_f32_e32 v111, v143, v7
	v_cvt_pk_bf16_f32 v110, v110, v111
	v_mul_f32_e32 v111, v112, v7
	v_mul_f32_e32 v7, v113, v7
	v_cvt_pk_bf16_f32 v111, v111, v7
	global_store_dwordx4 v[106:107], v[108:111], off offset:64 sc1

.Lew4_3:
	v_mov_b64_e32 v[106:107], v[126:127]
	v_mov_b64_e32 v[110:111], v[130:131]
	s_andn2_b64 vcc, exec, s[52:53]
	v_mov_b64_e32 v[108:109], v[128:129]
	v_mov_b64_e32 v[112:113], v[132:133]
	s_cbranch_vccnz .LBB0_1086
	v_ashrrev_i32_e32 v7, 31, v202
	v_lshrrev_b32_e32 v7, 19, v7
	v_add_u32_e32 v7, v202, v7
	v_and_b32_e32 v7, 0xffffe000, v7
	v_sub_u32_e32 v106, v202, v7
	v_ashrrev_i32_e32 v107, 31, v106
	v_lshlrev_b64 v[106:107], 7, v[106:107]
	v_lshl_add_u64 v[106:107], v[198:199], 0, v[106:107]
	global_load_dwordx4 v[110:113], v[106:107], off offset:16
	s_nop 0
	global_load_dwordx4 v[106:109], v[106:107], off
	v_mul_f32_e32 v7, v141, v141
	v_mul_f32_e32 v142, v137, v137
	v_fmac_f32_e32 v7, v140, v140
	v_fmac_f32_e32 v142, v136, v136
	v_add_f32_e32 v7, v7, v142
	v_mul_f32_e32 v142, v139, v139
	v_mul_f32_e32 v143, v135, v135
	v_fmac_f32_e32 v142, v138, v138
	v_fmac_f32_e32 v143, v134, v134
	v_add_f32_e32 v142, v142, v143
	v_add_f32_e32 v7, v7, v142
	v_mov_b32_e32 v142, v7
	s_nop 1
	v_permlane16_swap_b32_e32 v7, v142
	v_add_f32_e32 v7, v7, v142
	v_mov_b32_e32 v142, v7
	s_nop 1
	v_permlane32_swap_b32_e32 v7, v142
	v_add_f32_e32 v7, v7, v142
	v_fmamk_f32 v7, v7, 0x3d000000, v217
	v_rsq_f32_e32 v142, v7
	v_mov_b32_e32 v144, v140
	v_mov_b32_e32 v145, v138
	v_mov_b32_e32 v148, v38
	v_pk_mul_f32 v[144:145], v[144:145], v[142:143] op_sel_hi:[1,0]
	v_mov_b32_e32 v149, v34
	v_pk_mul_f32 v[144:145], v[148:149], v[144:145]
	s_nop 0
	v_pk_mul_f32 v[150:151], v[126:127], v[144:145]
	v_pk_mul_f32 v[144:145], v[126:127], v[144:145] op_sel:[1,0] op_sel_hi:[0,1]
	v_add_f32_e32 v143, v144, v145
	v_mov_b32_e32 v144, v141
	v_mov_b32_e32 v145, v139
	v_sub_f32_e32 v7, v150, v151
	v_pk_mul_f32 v[144:145], v[144:145], v[142:143] op_sel_hi:[1,0]
	v_mov_b32_e32 v150, v39
	v_mov_b32_e32 v151, v35
	v_pk_mul_f32 v[144:145], v[150:151], v[144:145]
	v_mul_f32_e32 v156, 0x3e16c740, v143
	v_pk_mul_f32 v[152:153], v[128:129], v[144:145]
	v_pk_mul_f32 v[144:145], v[128:129], v[144:145] op_sel:[1,0] op_sel_hi:[0,1]
	v_sub_f32_e32 v143, v152, v153
	v_mul_f32_e32 v157, 0x3e16c740, v143
	v_add_f32_e32 v143, v144, v145
	v_mov_b32_e32 v144, v136
	v_mov_b32_e32 v145, v134
	v_pk_mul_f32 v[144:145], v[144:145], v[142:143] op_sel_hi:[1,0]
	v_mov_b32_e32 v152, v40
	v_mov_b32_e32 v153, v36
	v_pk_mul_f32 v[144:145], v[152:153], v[144:145]
	v_mul_f32_e32 v158, 0x3e16c740, v143
	v_pk_mul_f32 v[154:155], v[130:131], v[144:145]
	v_pk_mul_f32 v[144:145], v[130:131], v[144:145] op_sel:[1,0] op_sel_hi:[0,1]
	v_sub_f32_e32 v143, v154, v155
	v_mul_f32_e32 v159, 0x3e16c740, v143
	v_add_f32_e32 v143, v144, v145
	v_mov_b32_e32 v144, v137
	v_mov_b32_e32 v145, v135
	v_mul_f32_e32 v160, 0x3e16c740, v143
	v_pk_mul_f32 v[142:143], v[144:145], v[142:143] op_sel_hi:[1,0]
	v_mov_b32_e32 v144, v41
	v_mov_b32_e32 v145, v37
	v_pk_mul_f32 v[142:143], v[144:145], v[142:143]
	v_mul_f32_e32 v7, 0x3e16c740, v7
	v_pk_mul_f32 v[154:155], v[132:133], v[142:143]
	v_pk_mul_f32 v[142:143], v[132:133], v[142:143] op_sel:[1,0] op_sel_hi:[0,1]
	v_add_f32_e32 v142, v142, v143
	v_mul_f32_e32 v161, 0x3e16c740, v142
	v_mov_b64_e32 v[142:143], s[28:29]
	v_sub_f32_e32 v154, v154, v155
	v_mad_i64_i32 v[142:143], s[0:1], v204, s70, v[142:143]
	v_mul_f32_e32 v155, 0x3e16c740, v154
	v_cvt_pk_bf16_f32 v154, v7, v157
	v_lshl_add_u64 v[142:143], v[8:9], 1, v[142:143]
	v_cvt_pk_bf16_f32 v155, v159, v155
	global_store_dwordx2 v[142:143], v[154:155], off offset:128 sc1
	v_cvt_pk_bf16_f32 v154, v156, v158
	v_mul_f32_e32 v7, v121, v121
	v_mul_f32_e32 v156, v117, v117
	v_fmac_f32_e32 v7, v120, v120
	v_fmac_f32_e32 v156, v116, v116
	v_add_f32_e32 v7, v7, v156
	v_mul_f32_e32 v156, v119, v119
	v_mul_f32_e32 v157, v115, v115
	v_fmac_f32_e32 v156, v118, v118
	v_fmac_f32_e32 v157, v114, v114
	v_add_f32_e32 v156, v156, v157
	v_add_f32_e32 v7, v7, v156
	v_mov_b32_e32 v156, v7
	s_nop 1
	v_permlane16_swap_b32_e32 v7, v156
	v_add_f32_e32 v7, v7, v156
	v_mov_b32_e32 v156, v7
	s_nop 1
	v_permlane32_swap_b32_e32 v7, v156
	v_add_f32_e32 v7, v7, v156
	v_fmamk_f32 v7, v7, 0x3d000000, v217
	v_rsq_f32_e32 v156, v7
	v_cvt_pk_bf16_f32 v155, v160, v161
	global_store_dwordx2 v[142:143], v[154:155], off offset:160 sc1
	v_mov_b32_e32 v154, v120
	v_mov_b32_e32 v155, v118
	v_pk_mul_f32 v[154:155], v[154:155], v[156:157] op_sel_hi:[1,0]
	s_nop 0
	v_pk_mul_f32 v[148:149], v[148:149], v[154:155]
	s_nop 0
	v_pk_mul_f32 v[154:155], v[126:127], v[148:149]
	v_pk_mul_f32 v[148:149], v[126:127], v[148:149] op_sel:[1,0] op_sel_hi:[0,1]
	v_add_f32_e32 v148, v148, v149
	v_sub_f32_e32 v7, v154, v155
	v_mul_f32_e32 v154, 0x3e16c740, v148
	v_mov_b32_e32 v148, v121
	v_mov_b32_e32 v149, v119
	v_pk_mul_f32 v[148:149], v[148:149], v[156:157] op_sel_hi:[1,0]
	v_mul_f32_e32 v7, 0x3e16c740, v7
	v_pk_mul_f32 v[148:149], v[150:151], v[148:149]
	s_nop 0
	v_pk_mul_f32 v[150:151], v[128:129], v[148:149]
	v_pk_mul_f32 v[148:149], v[128:129], v[148:149] op_sel:[1,0] op_sel_hi:[0,1]
	v_add_f32_e32 v148, v148, v149
	v_mul_f32_e32 v157, 0x3e16c740, v148
	v_mov_b32_e32 v148, v116
	v_mov_b32_e32 v149, v114
	v_pk_mul_f32 v[148:149], v[148:149], v[156:157] op_sel_hi:[1,0]
	v_sub_f32_e32 v150, v150, v151
	v_pk_mul_f32 v[148:149], v[152:153], v[148:149]
	v_mul_f32_e32 v155, 0x3e16c740, v150
	v_pk_mul_f32 v[150:151], v[130:131], v[148:149]
	v_pk_mul_f32 v[148:149], v[130:131], v[148:149] op_sel:[1,0] op_sel_hi:[0,1]
	v_add_f32_e32 v148, v148, v149
	v_sub_f32_e32 v150, v150, v151
	v_mul_f32_e32 v151, 0x3e16c740, v148
	v_mov_b32_e32 v148, v117
	v_mov_b32_e32 v149, v115
	v_pk_mul_f32 v[148:149], v[148:149], v[156:157] op_sel_hi:[1,0]
	v_mul_f32_e32 v150, 0x3e16c740, v150
	v_pk_mul_f32 v[144:145], v[144:145], v[148:149]
	s_nop 0
	v_pk_mul_f32 v[148:149], v[132:133], v[144:145]
	v_pk_mul_f32 v[144:145], v[132:133], v[144:145] op_sel:[1,0] op_sel_hi:[0,1]
	v_sub_f32_e32 v148, v148, v149
	v_add_f32_e32 v144, v144, v145
	v_mul_f32_e32 v148, 0x3e16c740, v148
	v_mul_f32_e32 v149, 0x3e16c740, v144
	v_cvt_pk_bf16_f32 v144, v7, v155
	v_cvt_pk_bf16_f32 v145, v150, v148
	global_store_dwordx2 v[142:143], v[144:145], off offset:320 sc1
	v_cvt_pk_bf16_f32 v144, v154, v157
	v_cvt_pk_bf16_f32 v145, v151, v149
	global_store_dwordx2 v[142:143], v[144:145], off offset:352 sc1

.Lew4_4:
	v_mul_f32_e32 v106, v137, v137
	v_fmac_f32_e32 v7, v140, v140
	v_fmac_f32_e32 v106, v136, v136
	v_add_f32_e32 v7, v7, v106
	v_mul_f32_e32 v106, v139, v139
	v_mul_f32_e32 v107, v135, v135
	v_fmac_f32_e32 v106, v138, v138
	v_fmac_f32_e32 v107, v134, v134
	v_add_f32_e32 v106, v106, v107
	v_add_f32_e32 v7, v7, v106
	v_mul_f32_e32 v106, v121, v121
	v_mul_f32_e32 v107, v117, v117
	v_fmac_f32_e32 v106, v120, v120
	v_fmac_f32_e32 v107, v116, v116
	v_add_f32_e32 v106, v106, v107
	v_mul_f32_e32 v107, v119, v119
	v_mul_f32_e32 v108, v115, v115
	v_fmac_f32_e32 v107, v118, v118
	v_fmac_f32_e32 v108, v114, v114
	v_add_f32_e32 v107, v107, v108
	v_add_f32_e32 v106, v106, v107
	v_add_f32_e32 v7, v7, v106
	v_mov_b32_e32 v106, v7
	s_nop 1
	v_permlane16_swap_b32_e32 v7, v106
	v_add_f32_e32 v7, v7, v106
	v_mov_b32_e32 v106, v7
	s_nop 1
	v_permlane32_swap_b32_e32 v7, v106
	v_add_f32_e32 v7, v7, v106
	v_fmamk_f32 v7, v7, 0x3c800000, v217
	v_rsq_f32_e32 v7, v7
	v_pk_mul_f32 v[106:107], v[38:39], v[140:141]
	v_pk_mul_f32 v[108:109], v[40:41], v[136:137]
	v_pk_mul_f32 v[112:113], v[36:37], v[134:135]
	v_mul_f32_e32 v7, 0x3e16c740, v7
	v_mul_f32_e32 v106, v106, v7
	v_mul_f32_e32 v107, v107, v7
	v_pk_mul_f32 v[134:135], v[34:35], v[138:139]
	v_cvt_pk_bf16_f32 v106, v106, v107
	v_mul_f32_e32 v107, v108, v7
	v_mul_f32_e32 v108, v109, v7
	v_cvt_pk_bf16_f32 v107, v107, v108
	v_mul_f32_e32 v108, v134, v7
	v_mul_f32_e32 v109, v135, v7
	v_mad_i64_i32 v[110:111], s[0:1], v204, s70, v[146:147]
	v_cvt_pk_bf16_f32 v108, v108, v109
	v_mul_f32_e32 v109, v112, v7
	v_mul_f32_e32 v112, v113, v7
	v_cvt_pk_bf16_f32 v109, v109, v112
	global_store_dwordx4 v[110:111], v[106:109], off sc1
	v_pk_mul_f32 v[112:113], v[28:29], v[114:115]
	v_pk_mul_f32 v[114:115], v[26:27], v[118:119]
	v_pk_mul_f32 v[106:107], v[30:31], v[120:121]
	v_pk_mul_f32 v[108:109], v[32:33], v[116:117]
	v_mul_f32_e32 v106, v106, v7
	v_mul_f32_e32 v107, v107, v7
	v_cvt_pk_bf16_f32 v106, v106, v107
	v_mul_f32_e32 v107, v108, v7
	v_mul_f32_e32 v108, v109, v7
	v_cvt_pk_bf16_f32 v107, v107, v108
	v_mul_f32_e32 v108, v114, v7
	v_mul_f32_e32 v109, v115, v7
	v_cvt_pk_bf16_f32 v108, v108, v109
	v_mul_f32_e32 v109, v112, v7
	v_mul_f32_e32 v7, v113, v7
	v_cvt_pk_bf16_f32 v109, v109, v7
	global_store_dwordx4 v[110:111], v[106:109], off offset:64 sc1
	v_mov_b64_e32 v[110:111], v[130:131]
	v_mov_b64_e32 v[112:113], v[132:133]
	v_mov_b64_e32 v[106:107], v[126:127]
	v_mov_b64_e32 v[108:109], v[128:129]
.LBB0_1089:
	v_add_f32_e32 v7, v122, v123
	v_add_f32_e32 v114, v124, v125
	v_add_f32_e32 v7, v7, v114
	v_fmaak_f32 v7, v3, v7, 0x358637bd
	v_rsq_f32_e32 v122, v7
	s_and_b64 vcc, exec, s[8:9]
	s_mov_b64 s[52:53], -1
	v_pk_mul_f32 v[116:117], v[104:105], v[122:123] op_sel_hi:[1,0]
	v_pk_mul_f32 v[120:121], v[102:103], v[122:123] op_sel_hi:[1,0]
	v_pk_mul_f32 v[114:115], v[100:101], v[122:123] op_sel_hi:[1,0]
	v_pk_mul_f32 v[118:119], v[98:99], v[122:123] op_sel_hi:[1,0]
	v_pk_mul_f32 v[96:97], v[96:97], v[122:123] op_sel_hi:[1,0]
	v_pk_mul_f32 v[94:95], v[94:95], v[122:123] op_sel_hi:[1,0]
	v_pk_mul_f32 v[92:93], v[92:93], v[122:123] op_sel_hi:[1,0]
	v_pk_mul_f32 v[90:91], v[90:91], v[122:123] op_sel_hi:[1,0]
	s_cbranch_vccnz .LBB0_1099
	s_and_b64 vcc, exec, s[6:7]
	s_cbranch_vccnz .LBB0_1096
	v_lshlrev_b64 v[98:99], 11, v[202:203]
	v_lshl_add_u64 v[98:99], v[4:5], 0, v[98:99]
	s_andn2_b64 vcc, exec, s[26:27]
	s_cbranch_vccnz .LBB0_1093
	v_cvt_pk_bf16_f32 v100, v120, v121
	v_cvt_pk_bf16_f32 v101, v116, v117
	v_cvt_pk_bf16_f32 v102, v118, v119
	v_cvt_pk_bf16_f32 v103, v114, v115
	s_mov_b64 s[52:53], 0
	global_store_dwordx4 v[98:99], v[100:103], off sc1
	s_nop 1
	v_cvt_pk_bf16_f32 v100, v94, v95
	v_cvt_pk_bf16_f32 v101, v96, v97
	v_cvt_pk_bf16_f32 v102, v90, v91
	v_cvt_pk_bf16_f32 v103, v92, v93
	global_store_dwordx4 v[98:99], v[100:103], off offset:64 sc1
.LBB0_1093:
	s_andn2_b64 vcc, exec, s[52:53]
	s_cbranch_vccnz .LBB0_1095
	v_mul_f32_e32 v7, v121, v121
	v_mul_f32_e32 v100, v117, v117
	v_fmac_f32_e32 v7, v120, v120
	v_fmac_f32_e32 v100, v116, v116
	v_add_f32_e32 v7, v7, v100
	v_mul_f32_e32 v100, v119, v119
	v_mul_f32_e32 v101, v115, v115
	v_fmac_f32_e32 v100, v118, v118
	v_fmac_f32_e32 v101, v114, v114
	v_add_f32_e32 v100, v100, v101
	v_add_f32_e32 v7, v7, v100
	v_mul_f32_e32 v100, v95, v95
	v_mul_f32_e32 v101, v97, v97
	v_fmac_f32_e32 v100, v94, v94
	v_fmac_f32_e32 v101, v96, v96
	v_add_f32_e32 v100, v100, v101
	v_mul_f32_e32 v101, v91, v91
	v_mul_f32_e32 v102, v93, v93
	v_fmac_f32_e32 v101, v90, v90
	v_fmac_f32_e32 v102, v92, v92
	v_add_f32_e32 v101, v101, v102
	v_add_f32_e32 v100, v100, v101
	v_add_f32_e32 v7, v7, v100
	v_mov_b32_e32 v100, v7
	s_nop 1
	v_permlane16_swap_b32_e32 v7, v100
	v_add_f32_e32 v7, v7, v100
	v_mov_b32_e32 v100, v7
	s_nop 1
	v_permlane32_swap_b32_e32 v7, v100
	v_add_f32_e32 v7, v7, v100
	v_fmamk_f32 v7, v7, 0x3c800000, v217
	v_rsq_f32_e32 v7, v7
	v_pk_mul_f32 v[100:101], v[38:39], v[120:121]
	v_pk_mul_f32 v[102:103], v[40:41], v[116:117]
	v_pk_mul_f32 v[122:123], v[34:35], v[118:119]
	v_mul_f32_e32 v100, v100, v7
	v_mul_f32_e32 v101, v101, v7
	v_cvt_pk_bf16_f32 v100, v100, v101
	v_mul_f32_e32 v101, v102, v7
	v_mul_f32_e32 v102, v103, v7
	v_pk_mul_f32 v[104:105], v[36:37], v[114:115]
	v_cvt_pk_bf16_f32 v101, v101, v102
	v_mul_f32_e32 v102, v122, v7
	v_mul_f32_e32 v103, v123, v7
	v_cvt_pk_bf16_f32 v102, v102, v103
	v_mul_f32_e32 v103, v104, v7
	v_mul_f32_e32 v104, v105, v7
	v_cvt_pk_bf16_f32 v103, v103, v104
	global_store_dwordx4 v[98:99], v[100:103], off sc1
	v_pk_mul_f32 v[122:123], v[26:27], v[90:91]
	v_pk_mul_f32 v[104:105], v[28:29], v[92:93]
	v_pk_mul_f32 v[100:101], v[30:31], v[94:95]
	v_pk_mul_f32 v[102:103], v[32:33], v[96:97]
	v_mul_f32_e32 v100, v100, v7
	v_mul_f32_e32 v101, v101, v7
	v_cvt_pk_bf16_f32 v100, v100, v101
	v_mul_f32_e32 v101, v102, v7
	v_mul_f32_e32 v102, v103, v7
	v_cvt_pk_bf16_f32 v101, v101, v102
	v_mul_f32_e32 v102, v122, v7
	v_mul_f32_e32 v103, v123, v7
	v_cvt_pk_bf16_f32 v102, v102, v103
	v_mul_f32_e32 v103, v104, v7
	v_mul_f32_e32 v7, v105, v7
	v_cvt_pk_bf16_f32 v103, v103, v7
	global_store_dwordx4 v[98:99], v[100:103], off offset:64 sc1

.Lew4_5:
	v_mov_b64_e32 v[98:99], v[106:107]
	v_mov_b64_e32 v[102:103], v[110:111]
	s_andn2_b64 vcc, exec, s[52:53]
	v_mov_b64_e32 v[100:101], v[108:109]
	v_mov_b64_e32 v[104:105], v[112:113]
	s_cbranch_vccnz .LBB0_1098
	v_add_u32_e32 v7, 0x80, v200
	v_ashrrev_i32_e32 v98, 31, v7
	v_lshrrev_b32_e32 v98, 19, v98
	v_add_u32_e32 v98, v7, v98
	v_and_b32_e32 v98, 0xffffe000, v98
	v_sub_u32_e32 v98, v7, v98
	v_ashrrev_i32_e32 v99, 31, v98
	v_lshlrev_b64 v[98:99], 7, v[98:99]
	v_lshl_add_u64 v[98:99], v[198:199], 0, v[98:99]
	global_load_dwordx4 v[102:105], v[98:99], off offset:16
	s_nop 0
	global_load_dwordx4 v[98:101], v[98:99], off
	v_mul_f32_e32 v7, v121, v121
	v_mul_f32_e32 v122, v117, v117
	v_fmac_f32_e32 v7, v120, v120
	v_fmac_f32_e32 v122, v116, v116
	v_add_f32_e32 v7, v7, v122
	v_mul_f32_e32 v122, v119, v119
	v_mul_f32_e32 v123, v115, v115
	v_fmac_f32_e32 v122, v118, v118
	v_fmac_f32_e32 v123, v114, v114
	v_add_f32_e32 v122, v122, v123
	v_add_f32_e32 v7, v7, v122
	v_mov_b32_e32 v122, v7
	s_nop 1
	v_permlane16_swap_b32_e32 v7, v122
	v_add_f32_e32 v7, v7, v122
	v_mov_b32_e32 v122, v7
	s_nop 1
	v_permlane32_swap_b32_e32 v7, v122
	v_add_f32_e32 v7, v7, v122
	v_fmamk_f32 v7, v7, 0x3d000000, v217
	v_rsq_f32_e32 v122, v7
	v_mov_b32_e32 v124, v120
	v_mov_b32_e32 v125, v118
	v_mov_b32_e32 v126, v38
	v_pk_mul_f32 v[124:125], v[124:125], v[122:123] op_sel_hi:[1,0]
	v_mov_b32_e32 v127, v34
	v_pk_mul_f32 v[124:125], v[126:127], v[124:125]
	s_nop 0
	v_pk_mul_f32 v[128:129], v[106:107], v[124:125]
	v_pk_mul_f32 v[124:125], v[106:107], v[124:125] op_sel:[1,0] op_sel_hi:[0,1]
	v_add_f32_e32 v123, v124, v125
	v_mov_b32_e32 v124, v121
	v_mov_b32_e32 v125, v119
	v_sub_f32_e32 v7, v128, v129
	v_pk_mul_f32 v[124:125], v[124:125], v[122:123] op_sel_hi:[1,0]
	v_mov_b32_e32 v128, v39
	v_mov_b32_e32 v129, v35
	v_pk_mul_f32 v[124:125], v[128:129], v[124:125]
	v_mul_f32_e32 v134, 0x3e16c740, v123
	v_pk_mul_f32 v[130:131], v[108:109], v[124:125]
	v_pk_mul_f32 v[124:125], v[108:109], v[124:125] op_sel:[1,0] op_sel_hi:[0,1]
	v_sub_f32_e32 v123, v130, v131
	v_mul_f32_e32 v135, 0x3e16c740, v123
	v_add_f32_e32 v123, v124, v125
	v_mov_b32_e32 v124, v116
	v_mov_b32_e32 v125, v114
	v_pk_mul_f32 v[124:125], v[124:125], v[122:123] op_sel_hi:[1,0]
	v_mov_b32_e32 v130, v40
	v_mov_b32_e32 v131, v36
	v_pk_mul_f32 v[124:125], v[130:131], v[124:125]
	v_mul_f32_e32 v136, 0x3e16c740, v123
	v_pk_mul_f32 v[132:133], v[110:111], v[124:125]
	v_pk_mul_f32 v[124:125], v[110:111], v[124:125] op_sel:[1,0] op_sel_hi:[0,1]
	v_sub_f32_e32 v123, v132, v133
	v_mul_f32_e32 v137, 0x3e16c740, v123
	v_add_f32_e32 v123, v124, v125
	v_mov_b32_e32 v124, v117
	v_mov_b32_e32 v125, v115
	v_mul_f32_e32 v138, 0x3e16c740, v123
	v_pk_mul_f32 v[122:123], v[124:125], v[122:123] op_sel_hi:[1,0]
	v_mov_b32_e32 v124, v41
	v_mov_b32_e32 v125, v37
	v_pk_mul_f32 v[122:123], v[124:125], v[122:123]
	v_mul_f32_e32 v7, 0x3e16c740, v7
	v_pk_mul_f32 v[132:133], v[112:113], v[122:123]
	v_pk_mul_f32 v[122:123], v[112:113], v[122:123] op_sel:[1,0] op_sel_hi:[0,1]
	v_add_f32_e32 v122, v122, v123
	v_mul_f32_e32 v139, 0x3e16c740, v122
	v_mov_b64_e32 v[122:123], s[28:29]
	v_sub_f32_e32 v132, v132, v133
	v_mad_i64_i32 v[122:123], s[0:1], v202, s70, v[122:123]
	v_mul_f32_e32 v133, 0x3e16c740, v132
	v_cvt_pk_bf16_f32 v132, v7, v135
	v_lshl_add_u64 v[122:123], v[8:9], 1, v[122:123]
	v_cvt_pk_bf16_f32 v133, v137, v133
	global_store_dwordx2 v[122:123], v[132:133], off offset:128 sc1
	v_cvt_pk_bf16_f32 v132, v134, v136
	v_mul_f32_e32 v7, v95, v95
	v_mul_f32_e32 v134, v97, v97
	v_fmac_f32_e32 v7, v94, v94
	v_fmac_f32_e32 v134, v96, v96
	v_add_f32_e32 v7, v7, v134
	v_mul_f32_e32 v134, v91, v91
	v_mul_f32_e32 v135, v93, v93
	v_fmac_f32_e32 v134, v90, v90
	v_fmac_f32_e32 v135, v92, v92
	v_add_f32_e32 v134, v134, v135
	v_add_f32_e32 v7, v7, v134
	v_mov_b32_e32 v134, v7
	s_nop 1
	v_permlane16_swap_b32_e32 v7, v134
	v_add_f32_e32 v7, v7, v134
	v_mov_b32_e32 v134, v7
	s_nop 1
	v_permlane32_swap_b32_e32 v7, v134
	v_add_f32_e32 v7, v7, v134
	v_fmamk_f32 v7, v7, 0x3d000000, v217
	v_rsq_f32_e32 v134, v7
	v_cvt_pk_bf16_f32 v133, v138, v139
	global_store_dwordx2 v[122:123], v[132:133], off offset:160 sc1
	v_mov_b32_e32 v132, v94
	v_mov_b32_e32 v133, v90
	v_pk_mul_f32 v[132:133], v[132:133], v[134:135] op_sel_hi:[1,0]
	s_nop 0
	v_pk_mul_f32 v[126:127], v[126:127], v[132:133]
	s_nop 0
	v_pk_mul_f32 v[132:133], v[106:107], v[126:127]
	v_pk_mul_f32 v[126:127], v[106:107], v[126:127] op_sel:[1,0] op_sel_hi:[0,1]
	v_add_f32_e32 v126, v126, v127
	v_sub_f32_e32 v7, v132, v133
	v_mul_f32_e32 v132, 0x3e16c740, v126
	v_mov_b32_e32 v126, v95
	v_mov_b32_e32 v127, v91
	v_pk_mul_f32 v[126:127], v[126:127], v[134:135] op_sel_hi:[1,0]
	v_mul_f32_e32 v7, 0x3e16c740, v7
	v_pk_mul_f32 v[126:127], v[128:129], v[126:127]
	s_nop 0
	v_pk_mul_f32 v[128:129], v[108:109], v[126:127]
	v_pk_mul_f32 v[126:127], v[108:109], v[126:127] op_sel:[1,0] op_sel_hi:[0,1]
	v_add_f32_e32 v126, v126, v127
	v_mul_f32_e32 v135, 0x3e16c740, v126
	v_mov_b32_e32 v126, v96
	v_mov_b32_e32 v127, v92
	v_pk_mul_f32 v[126:127], v[126:127], v[134:135] op_sel_hi:[1,0]
	v_sub_f32_e32 v128, v128, v129
	v_pk_mul_f32 v[126:127], v[130:131], v[126:127]
	v_mul_f32_e32 v133, 0x3e16c740, v128
	v_pk_mul_f32 v[128:129], v[110:111], v[126:127]
	v_pk_mul_f32 v[126:127], v[110:111], v[126:127] op_sel:[1,0] op_sel_hi:[0,1]
	v_add_f32_e32 v126, v126, v127
	v_sub_f32_e32 v128, v128, v129
	v_mul_f32_e32 v129, 0x3e16c740, v126
	v_mov_b32_e32 v126, v97
	v_mov_b32_e32 v127, v93
	v_pk_mul_f32 v[126:127], v[126:127], v[134:135] op_sel_hi:[1,0]
	v_mul_f32_e32 v128, 0x3e16c740, v128
	v_pk_mul_f32 v[124:125], v[124:125], v[126:127]
	s_nop 0
	v_pk_mul_f32 v[126:127], v[112:113], v[124:125]
	v_pk_mul_f32 v[124:125], v[112:113], v[124:125] op_sel:[1,0] op_sel_hi:[0,1]
	v_sub_f32_e32 v126, v126, v127
	v_add_f32_e32 v124, v124, v125
	v_mul_f32_e32 v126, 0x3e16c740, v126
	v_mul_f32_e32 v127, 0x3e16c740, v124
	v_cvt_pk_bf16_f32 v124, v7, v133
	v_cvt_pk_bf16_f32 v125, v128, v126
	global_store_dwordx2 v[122:123], v[124:125], off offset:320 sc1
	v_cvt_pk_bf16_f32 v124, v132, v135
	v_cvt_pk_bf16_f32 v125, v129, v127
	global_store_dwordx2 v[122:123], v[124:125], off offset:352 sc1

.Lew4_6:
	v_mul_f32_e32 v98, v117, v117
	v_fmac_f32_e32 v7, v120, v120
	v_fmac_f32_e32 v98, v116, v116
	v_add_f32_e32 v7, v7, v98
	v_mul_f32_e32 v98, v119, v119
	v_mul_f32_e32 v99, v115, v115
	v_fmac_f32_e32 v98, v118, v118
	v_fmac_f32_e32 v99, v114, v114
	v_add_f32_e32 v98, v98, v99
	v_add_f32_e32 v7, v7, v98
	v_mul_f32_e32 v98, v95, v95
	v_mul_f32_e32 v99, v97, v97
	v_fmac_f32_e32 v98, v94, v94
	v_fmac_f32_e32 v99, v96, v96
	v_add_f32_e32 v98, v98, v99
	v_mul_f32_e32 v99, v91, v91
	v_mul_f32_e32 v100, v93, v93
	v_fmac_f32_e32 v99, v90, v90
	v_fmac_f32_e32 v100, v92, v92
	v_add_f32_e32 v99, v99, v100
	v_add_f32_e32 v98, v98, v99
	v_add_f32_e32 v7, v7, v98
	v_mov_b32_e32 v98, v7
	s_nop 1
	v_permlane16_swap_b32_e32 v7, v98
	v_add_f32_e32 v7, v7, v98
	v_mov_b32_e32 v98, v7
	s_nop 1
	v_permlane32_swap_b32_e32 v7, v98
	v_add_f32_e32 v7, v7, v98
	v_fmamk_f32 v7, v7, 0x3c800000, v217
	v_rsq_f32_e32 v7, v7
	v_pk_mul_f32 v[98:99], v[38:39], v[120:121]
	v_pk_mul_f32 v[100:101], v[40:41], v[116:117]
	v_pk_mul_f32 v[104:105], v[36:37], v[114:115]
	v_mul_f32_e32 v7, 0x3e16c740, v7
	v_mul_f32_e32 v98, v98, v7
	v_mul_f32_e32 v99, v99, v7
	v_pk_mul_f32 v[114:115], v[34:35], v[118:119]
	v_cvt_pk_bf16_f32 v98, v98, v99
	v_mul_f32_e32 v99, v100, v7
	v_mul_f32_e32 v100, v101, v7
	v_cvt_pk_bf16_f32 v99, v99, v100
	v_mul_f32_e32 v100, v114, v7
	v_mul_f32_e32 v101, v115, v7
	v_mad_i64_i32 v[102:103], s[0:1], v202, s70, v[146:147]
	v_cvt_pk_bf16_f32 v100, v100, v101
	v_mul_f32_e32 v101, v104, v7
	v_pk_mul_f32 v[94:95], v[30:31], v[94:95]
	v_mul_f32_e32 v104, v105, v7
	v_cvt_pk_bf16_f32 v101, v101, v104
	global_store_dwordx4 v[102:103], v[98:101], off sc1
	v_pk_mul_f32 v[96:97], v[32:33], v[96:97]
	s_nop 0
	v_pk_mul_f32 v[98:99], v[28:29], v[92:93]
	v_pk_mul_f32 v[92:93], v[26:27], v[90:91]
	v_mul_f32_e32 v90, v94, v7
	v_mul_f32_e32 v91, v95, v7
	v_cvt_pk_bf16_f32 v90, v90, v91
	v_mul_f32_e32 v91, v96, v7
	v_mul_f32_e32 v92, v92, v7
	v_mul_f32_e32 v93, v93, v7
	v_mul_f32_e32 v94, v97, v7
	v_cvt_pk_bf16_f32 v91, v91, v94
	v_cvt_pk_bf16_f32 v92, v92, v93
	v_mul_f32_e32 v93, v98, v7
	v_mul_f32_e32 v7, v99, v7
	v_cvt_pk_bf16_f32 v93, v93, v7
	global_store_dwordx4 v[102:103], v[90:93], off offset:64 sc1
	v_mov_b64_e32 v[102:103], v[110:111]
	v_mov_b64_e32 v[98:99], v[106:107]
	v_mov_b64_e32 v[104:105], v[112:113]
	v_mov_b64_e32 v[100:101], v[108:109]

.Lew4_8:
	v_mov_b32_e32 v122, v119
	v_mov_b32_e32 v123, v120
	v_mov_b32_e32 v119, v121
	v_pk_add_f32 v[118:119], v[122:123], v[118:119]
	s_nop 0
	v_add_f32_e32 v7, v118, v119
	v_fmaak_f32 v7, v3, v7, 0x358637bd
	v_rsq_f32_e32 v126, v7
	s_nop 0
	v_pk_mul_f32 v[122:123], v[88:89], v[126:127] op_sel_hi:[1,0]
	v_pk_mul_f32 v[124:125], v[86:87], v[126:127] op_sel_hi:[1,0]
	v_pk_mul_f32 v[118:119], v[84:85], v[126:127] op_sel_hi:[1,0]
	v_pk_mul_f32 v[120:121], v[82:83], v[126:127] op_sel_hi:[1,0]
	v_pk_mul_f32 v[86:87], v[80:81], v[126:127] op_sel_hi:[1,0]
	v_pk_mul_f32 v[88:89], v[78:79], v[126:127] op_sel_hi:[1,0]
	v_pk_mul_f32 v[82:83], v[76:77], v[126:127] op_sel_hi:[1,0]
	v_pk_mul_f32 v[84:85], v[74:75], v[126:127] op_sel_hi:[1,0]
	s_cbranch_vccnz .LBB0_1111
	s_and_b64 vcc, exec, s[6:7]
	s_cbranch_vccnz .LBB0_1108
	v_lshlrev_b64 v[74:75], 11, v[116:117]
	v_lshl_add_u64 v[74:75], v[4:5], 0, v[74:75]
	s_andn2_b64 vcc, exec, s[26:27]
	s_cbranch_vccnz .LBB0_1105
	v_cvt_pk_bf16_f32 v76, v124, v125
	v_cvt_pk_bf16_f32 v77, v122, v123
	v_cvt_pk_bf16_f32 v78, v120, v121
	v_cvt_pk_bf16_f32 v79, v118, v119
	s_mov_b64 s[50:51], 0
	global_store_dwordx4 v[74:75], v[76:79], off sc1
	s_nop 1
	v_cvt_pk_bf16_f32 v76, v88, v89
	v_cvt_pk_bf16_f32 v77, v86, v87
	v_cvt_pk_bf16_f32 v78, v84, v85
	v_cvt_pk_bf16_f32 v79, v82, v83
	global_store_dwordx4 v[74:75], v[76:79], off offset:64 sc1
.LBB0_1105:
	s_andn2_b64 vcc, exec, s[50:51]
	s_cbranch_vccnz .LBB0_1107
	v_mul_f32_e32 v7, v125, v125
	v_mul_f32_e32 v76, v123, v123
	v_fmac_f32_e32 v7, v124, v124
	v_fmac_f32_e32 v76, v122, v122
	v_add_f32_e32 v7, v7, v76
	v_mul_f32_e32 v76, v121, v121
	v_mul_f32_e32 v77, v119, v119
	v_fmac_f32_e32 v76, v120, v120
	v_fmac_f32_e32 v77, v118, v118
	v_add_f32_e32 v76, v76, v77
	v_add_f32_e32 v7, v7, v76
	v_mul_f32_e32 v76, v89, v89
	v_mul_f32_e32 v77, v87, v87
	v_fmac_f32_e32 v76, v88, v88
	v_fmac_f32_e32 v77, v86, v86
	v_add_f32_e32 v76, v76, v77
	v_mul_f32_e32 v77, v85, v85
	v_mul_f32_e32 v78, v83, v83
	v_fmac_f32_e32 v77, v84, v84
	v_fmac_f32_e32 v78, v82, v82
	v_add_f32_e32 v77, v77, v78
	v_add_f32_e32 v76, v76, v77
	v_add_f32_e32 v7, v7, v76
	v_mov_b32_e32 v76, v7
	s_nop 1
	v_permlane16_swap_b32_e32 v7, v76
	v_add_f32_e32 v7, v7, v76
	v_mov_b32_e32 v76, v7
	s_nop 1
	v_permlane32_swap_b32_e32 v7, v76
	v_add_f32_e32 v7, v7, v76
	v_fmamk_f32 v7, v7, 0x3c800000, v217
	v_rsq_f32_e32 v7, v7
	v_pk_mul_f32 v[76:77], v[38:39], v[124:125]
	v_pk_mul_f32 v[78:79], v[40:41], v[122:123]
	v_pk_mul_f32 v[126:127], v[34:35], v[120:121]
	v_mul_f32_e32 v76, v76, v7
	v_mul_f32_e32 v77, v77, v7
	v_cvt_pk_bf16_f32 v76, v76, v77
	v_mul_f32_e32 v77, v78, v7
	v_mul_f32_e32 v78, v79, v7
	v_pk_mul_f32 v[80:81], v[36:37], v[118:119]
	v_cvt_pk_bf16_f32 v77, v77, v78
	v_mul_f32_e32 v78, v126, v7
	v_mul_f32_e32 v79, v127, v7
	v_cvt_pk_bf16_f32 v78, v78, v79
	v_mul_f32_e32 v79, v80, v7
	v_mul_f32_e32 v80, v81, v7
	v_cvt_pk_bf16_f32 v79, v79, v80
	global_store_dwordx4 v[74:75], v[76:79], off sc1
	v_pk_mul_f32 v[126:127], v[26:27], v[84:85]
	v_pk_mul_f32 v[80:81], v[28:29], v[82:83]
	v_pk_mul_f32 v[76:77], v[30:31], v[88:89]
	v_pk_mul_f32 v[78:79], v[32:33], v[86:87]
	v_mul_f32_e32 v76, v76, v7
	v_mul_f32_e32 v77, v77, v7
	v_cvt_pk_bf16_f32 v76, v76, v77
	v_mul_f32_e32 v77, v78, v7
	v_mul_f32_e32 v78, v79, v7
	v_cvt_pk_bf16_f32 v77, v77, v78
	v_mul_f32_e32 v78, v126, v7
	v_mul_f32_e32 v79, v127, v7
	v_cvt_pk_bf16_f32 v78, v78, v79
	v_mul_f32_e32 v79, v80, v7
	v_mul_f32_e32 v7, v81, v7
	v_cvt_pk_bf16_f32 v79, v79, v7
	global_store_dwordx4 v[74:75], v[76:79], off offset:64 sc1

.LBB0_1108:
	v_mov_b64_e32 v[74:75], v[98:99]
	v_mov_b64_e32 v[78:79], v[102:103]
	s_andn2_b64 vcc, exec, s[50:51]
	v_mov_b64_e32 v[76:77], v[100:101]
	v_mov_b64_e32 v[80:81], v[104:105]
	s_cbranch_vccnz .LBB0_1110
	v_ashrrev_i32_e32 v7, 31, v114
	v_lshrrev_b32_e32 v7, 19, v7
	v_add_u32_e32 v7, v114, v7
	v_and_b32_e32 v7, 0xffffe000, v7
	v_sub_u32_e32 v74, v114, v7
	v_ashrrev_i32_e32 v75, 31, v74
	v_lshlrev_b64 v[74:75], 7, v[74:75]
	v_lshl_add_u64 v[74:75], v[198:199], 0, v[74:75]
	global_load_dwordx4 v[78:81], v[74:75], off offset:16
	s_nop 0
	global_load_dwordx4 v[74:77], v[74:75], off
	v_mul_f32_e32 v7, v125, v125
	v_mul_f32_e32 v117, v123, v123
	v_fmac_f32_e32 v7, v124, v124
	v_fmac_f32_e32 v117, v122, v122
	v_add_f32_e32 v7, v7, v117
	v_mul_f32_e32 v117, v121, v121
	v_mul_f32_e32 v126, v119, v119
	v_fmac_f32_e32 v117, v120, v120
	v_fmac_f32_e32 v126, v118, v118
	v_add_f32_e32 v117, v117, v126
	v_add_f32_e32 v7, v7, v117
	v_mov_b32_e32 v117, v7
	s_nop 1
	v_permlane16_swap_b32_e32 v7, v117
	v_add_f32_e32 v7, v7, v117
	v_mov_b32_e32 v117, v7
	s_nop 1
	v_permlane32_swap_b32_e32 v7, v117
	v_add_f32_e32 v7, v7, v117
	v_fmamk_f32 v7, v7, 0x3d000000, v217
	v_rsq_f32_e32 v126, v7
	v_mov_b32_e32 v128, v124
	v_mov_b32_e32 v129, v120
	v_mov_b32_e32 v130, v38
	v_pk_mul_f32 v[128:129], v[128:129], v[126:127] op_sel_hi:[1,0]
	v_mov_b32_e32 v131, v34
	v_pk_mul_f32 v[128:129], v[130:131], v[128:129]
	s_nop 0
	v_pk_mul_f32 v[132:133], v[98:99], v[128:129]
	v_pk_mul_f32 v[128:129], v[98:99], v[128:129] op_sel:[1,0] op_sel_hi:[0,1]
	v_add_f32_e32 v117, v128, v129
	v_mov_b32_e32 v128, v125
	v_mov_b32_e32 v129, v121
	v_sub_f32_e32 v7, v132, v133
	v_pk_mul_f32 v[128:129], v[128:129], v[126:127] op_sel_hi:[1,0]
	v_mov_b32_e32 v132, v39
	v_mov_b32_e32 v133, v35
	v_pk_mul_f32 v[128:129], v[132:133], v[128:129]
	v_mul_f32_e32 v7, 0x3e16c740, v7
	v_pk_mul_f32 v[134:135], v[100:101], v[128:129]
	v_pk_mul_f32 v[128:129], v[100:101], v[128:129] op_sel:[1,0] op_sel_hi:[0,1]
	v_sub_f32_e32 v127, v134, v135
	v_mul_f32_e32 v138, 0x3e16c740, v127
	v_add_f32_e32 v127, v128, v129
	v_mov_b32_e32 v128, v122
	v_mov_b32_e32 v129, v118
	v_pk_mul_f32 v[128:129], v[128:129], v[126:127] op_sel_hi:[1,0]
	v_mov_b32_e32 v134, v40
	v_mov_b32_e32 v135, v36
	v_pk_mul_f32 v[128:129], v[134:135], v[128:129]
	v_mul_f32_e32 v139, 0x3e16c740, v127
	v_pk_mul_f32 v[136:137], v[102:103], v[128:129]
	v_pk_mul_f32 v[128:129], v[102:103], v[128:129] op_sel:[1,0] op_sel_hi:[0,1]
	v_sub_f32_e32 v127, v136, v137
	v_mul_f32_e32 v140, 0x3e16c740, v127
	v_add_f32_e32 v127, v128, v129
	v_mov_b32_e32 v128, v123
	v_mov_b32_e32 v129, v119
	v_mul_f32_e32 v141, 0x3e16c740, v127
	v_pk_mul_f32 v[126:127], v[128:129], v[126:127] op_sel_hi:[1,0]
	v_mov_b32_e32 v128, v41
	v_mov_b32_e32 v129, v37
	v_pk_mul_f32 v[126:127], v[128:129], v[126:127]
	v_mul_f32_e32 v117, 0x3e16c740, v117
	v_pk_mul_f32 v[136:137], v[104:105], v[126:127]
	v_pk_mul_f32 v[126:127], v[104:105], v[126:127] op_sel:[1,0] op_sel_hi:[0,1]
	v_add_f32_e32 v126, v126, v127
	v_mul_f32_e32 v142, 0x3e16c740, v126
	v_mov_b64_e32 v[126:127], s[28:29]
	v_sub_f32_e32 v136, v136, v137
	v_mad_i64_i32 v[126:127], s[0:1], v116, s70, v[126:127]
	v_mul_f32_e32 v137, 0x3e16c740, v136
	v_cvt_pk_bf16_f32 v136, v7, v138
	v_lshl_add_u64 v[126:127], v[8:9], 1, v[126:127]
	v_cvt_pk_bf16_f32 v137, v140, v137
	global_store_dwordx2 v[126:127], v[136:137], off offset:128 sc1
	v_cvt_pk_bf16_f32 v136, v117, v139
	v_mul_f32_e32 v7, v89, v89
	v_mul_f32_e32 v117, v87, v87
	v_fmac_f32_e32 v7, v88, v88
	v_fmac_f32_e32 v117, v86, v86
	v_add_f32_e32 v7, v7, v117
	v_mul_f32_e32 v117, v85, v85
	v_mul_f32_e32 v138, v83, v83
	v_fmac_f32_e32 v117, v84, v84
	v_fmac_f32_e32 v138, v82, v82
	v_add_f32_e32 v117, v117, v138
	v_add_f32_e32 v7, v7, v117
	v_mov_b32_e32 v117, v7
	s_nop 1
	v_permlane16_swap_b32_e32 v7, v117
	v_add_f32_e32 v7, v7, v117
	v_mov_b32_e32 v117, v7
	s_nop 1
	v_permlane32_swap_b32_e32 v7, v117
	v_add_f32_e32 v7, v7, v117
	v_fmamk_f32 v7, v7, 0x3d000000, v217
	v_rsq_f32_e32 v138, v7
	v_cvt_pk_bf16_f32 v137, v141, v142
	global_store_dwordx2 v[126:127], v[136:137], off offset:160 sc1
	v_mov_b32_e32 v136, v88
	v_mov_b32_e32 v137, v84
	v_pk_mul_f32 v[136:137], v[136:137], v[138:139] op_sel_hi:[1,0]
	s_nop 0
	v_pk_mul_f32 v[130:131], v[130:131], v[136:137]
	s_nop 0
	v_pk_mul_f32 v[136:137], v[98:99], v[130:131]
	v_pk_mul_f32 v[130:131], v[98:99], v[130:131] op_sel:[1,0] op_sel_hi:[0,1]
	v_add_f32_e32 v117, v130, v131
	v_mov_b32_e32 v130, v89
	v_mov_b32_e32 v131, v85
	v_pk_mul_f32 v[130:131], v[130:131], v[138:139] op_sel_hi:[1,0]
	v_sub_f32_e32 v7, v136, v137
	v_pk_mul_f32 v[130:131], v[132:133], v[130:131]
	v_mul_f32_e32 v7, 0x3e16c740, v7
	v_pk_mul_f32 v[132:133], v[100:101], v[130:131]
	v_pk_mul_f32 v[130:131], v[100:101], v[130:131] op_sel:[1,0] op_sel_hi:[0,1]
	v_add_f32_e32 v130, v130, v131
	v_mul_f32_e32 v137, 0x3e16c740, v130
	v_mov_b32_e32 v130, v86
	v_mov_b32_e32 v131, v82
	v_pk_mul_f32 v[130:131], v[130:131], v[138:139] op_sel_hi:[1,0]
	v_sub_f32_e32 v132, v132, v133
	v_pk_mul_f32 v[130:131], v[134:135], v[130:131]
	v_mul_f32_e32 v136, 0x3e16c740, v132
	v_pk_mul_f32 v[132:133], v[102:103], v[130:131]
	v_pk_mul_f32 v[130:131], v[102:103], v[130:131] op_sel:[1,0] op_sel_hi:[0,1]
	v_add_f32_e32 v130, v130, v131
	v_sub_f32_e32 v132, v132, v133
	v_mul_f32_e32 v133, 0x3e16c740, v130
	v_mov_b32_e32 v130, v87
	v_mov_b32_e32 v131, v83
	v_pk_mul_f32 v[130:131], v[130:131], v[138:139] op_sel_hi:[1,0]
	v_mul_f32_e32 v132, 0x3e16c740, v132
	v_pk_mul_f32 v[128:129], v[128:129], v[130:131]
	v_mul_f32_e32 v117, 0x3e16c740, v117
	v_pk_mul_f32 v[130:131], v[104:105], v[128:129]
	v_pk_mul_f32 v[128:129], v[104:105], v[128:129] op_sel:[1,0] op_sel_hi:[0,1]
	v_sub_f32_e32 v130, v130, v131
	v_add_f32_e32 v128, v128, v129
	v_mul_f32_e32 v130, 0x3e16c740, v130
	v_mul_f32_e32 v131, 0x3e16c740, v128
	v_cvt_pk_bf16_f32 v128, v7, v136
	v_cvt_pk_bf16_f32 v129, v132, v130
	global_store_dwordx2 v[126:127], v[128:129], off offset:320 sc1
	v_cvt_pk_bf16_f32 v128, v117, v137
	v_cvt_pk_bf16_f32 v129, v133, v131
	global_store_dwordx2 v[126:127], v[128:129], off offset:352 sc1

.Lew4_9:
	v_mul_f32_e32 v74, v123, v123
	v_fmac_f32_e32 v7, v124, v124
	v_fmac_f32_e32 v74, v122, v122
	v_add_f32_e32 v7, v7, v74
	v_mul_f32_e32 v74, v121, v121
	v_mul_f32_e32 v75, v119, v119
	v_fmac_f32_e32 v74, v120, v120
	v_fmac_f32_e32 v75, v118, v118
	v_add_f32_e32 v74, v74, v75
	v_add_f32_e32 v7, v7, v74
	v_mul_f32_e32 v74, v89, v89
	v_mul_f32_e32 v75, v87, v87
	v_fmac_f32_e32 v74, v88, v88
	v_fmac_f32_e32 v75, v86, v86
	v_add_f32_e32 v74, v74, v75
	v_mul_f32_e32 v75, v85, v85
	v_mul_f32_e32 v76, v83, v83
	v_fmac_f32_e32 v75, v84, v84
	v_fmac_f32_e32 v76, v82, v82
	v_add_f32_e32 v75, v75, v76
	v_add_f32_e32 v74, v74, v75
	v_add_f32_e32 v7, v7, v74
	v_mov_b32_e32 v74, v7
	s_nop 1
	v_permlane16_swap_b32_e32 v7, v74
	v_add_f32_e32 v7, v7, v74
	v_mov_b32_e32 v74, v7
	s_nop 1
	v_permlane32_swap_b32_e32 v7, v74
	v_add_f32_e32 v7, v7, v74
	v_fmamk_f32 v7, v7, 0x3c800000, v217
	v_rsq_f32_e32 v7, v7
	v_pk_mul_f32 v[74:75], v[38:39], v[124:125]
	v_pk_mul_f32 v[76:77], v[40:41], v[122:123]
	v_mad_i64_i32 v[78:79], s[0:1], v116, s70, v[146:147]
	v_mul_f32_e32 v7, 0x3e16c740, v7
	v_mul_f32_e32 v74, v74, v7
	v_mul_f32_e32 v75, v75, v7
	v_pk_mul_f32 v[116:117], v[34:35], v[120:121]
	v_cvt_pk_bf16_f32 v74, v74, v75
	v_mul_f32_e32 v75, v76, v7
	v_mul_f32_e32 v76, v77, v7
	v_pk_mul_f32 v[80:81], v[36:37], v[118:119]
	v_cvt_pk_bf16_f32 v75, v75, v76
	v_mul_f32_e32 v76, v116, v7
	v_mul_f32_e32 v77, v117, v7
	v_cvt_pk_bf16_f32 v76, v76, v77
	v_mul_f32_e32 v77, v80, v7
	v_mul_f32_e32 v80, v81, v7
	v_cvt_pk_bf16_f32 v77, v77, v80
	global_store_dwordx4 v[78:79], v[74:77], off sc1
	v_pk_mul_f32 v[80:81], v[28:29], v[82:83]
	v_pk_mul_f32 v[82:83], v[26:27], v[84:85]
	v_pk_mul_f32 v[74:75], v[30:31], v[88:89]
	v_pk_mul_f32 v[76:77], v[32:33], v[86:87]
	v_mul_f32_e32 v74, v74, v7
	v_mul_f32_e32 v75, v75, v7
	v_cvt_pk_bf16_f32 v74, v74, v75
	v_mul_f32_e32 v75, v76, v7
	v_mul_f32_e32 v76, v77, v7
	v_cvt_pk_bf16_f32 v75, v75, v76
	v_mul_f32_e32 v76, v82, v7
	v_mul_f32_e32 v77, v83, v7
	v_cvt_pk_bf16_f32 v76, v76, v77
	v_mul_f32_e32 v77, v80, v7
	v_mul_f32_e32 v7, v81, v7
	v_cvt_pk_bf16_f32 v77, v77, v7
	global_store_dwordx4 v[78:79], v[74:77], off offset:64 sc1
	v_mov_b64_e32 v[78:79], v[102:103]
	v_mov_b64_e32 v[80:81], v[104:105]
	v_mov_b64_e32 v[74:75], v[98:99]
	v_mov_b64_e32 v[76:77], v[100:101]

.Lew4_10:
	v_add_f32_e32 v7, v106, v107
	v_add_f32_e32 v82, v108, v109
	v_add_f32_e32 v7, v7, v82
	v_fmaak_f32 v7, v3, v7, 0x358637bd
	v_rsq_f32_e32 v98, v7
	s_and_b64 vcc, exec, s[8:9]
	s_mov_b64 s[50:51], -1
	v_pk_mul_f32 v[84:85], v[72:73], v[98:99] op_sel_hi:[1,0]
	v_pk_mul_f32 v[88:89], v[70:71], v[98:99] op_sel_hi:[1,0]
	v_pk_mul_f32 v[82:83], v[68:69], v[98:99] op_sel_hi:[1,0]
	v_pk_mul_f32 v[86:87], v[66:67], v[98:99] op_sel_hi:[1,0]
	v_pk_mul_f32 v[68:69], v[64:65], v[98:99] op_sel_hi:[1,0]
	v_pk_mul_f32 v[72:73], v[62:63], v[98:99] op_sel_hi:[1,0]
	v_pk_mul_f32 v[66:67], v[60:61], v[98:99] op_sel_hi:[1,0]
	v_pk_mul_f32 v[70:71], v[58:59], v[98:99] op_sel_hi:[1,0]
	s_cbranch_vccnz .LBB0_1123
	s_and_b64 vcc, exec, s[6:7]
	s_cbranch_vccnz .LBB0_1120
	v_lshlrev_b64 v[58:59], 11, v[114:115]
	v_lshl_add_u64 v[58:59], v[4:5], 0, v[58:59]
	s_andn2_b64 vcc, exec, s[26:27]
	s_cbranch_vccnz .LBB0_1117
	v_cvt_pk_bf16_f32 v60, v88, v89
	v_cvt_pk_bf16_f32 v61, v84, v85
	v_cvt_pk_bf16_f32 v62, v86, v87
	v_cvt_pk_bf16_f32 v63, v82, v83
	s_mov_b64 s[50:51], 0
	global_store_dwordx4 v[58:59], v[60:63], off sc1
	s_nop 1
	v_cvt_pk_bf16_f32 v60, v72, v73
	v_cvt_pk_bf16_f32 v61, v68, v69
	v_cvt_pk_bf16_f32 v62, v70, v71
	v_cvt_pk_bf16_f32 v63, v66, v67
	global_store_dwordx4 v[58:59], v[60:63], off offset:64 sc1
.LBB0_1117:
	s_andn2_b64 vcc, exec, s[50:51]
	s_cbranch_vccnz .LBB0_1119
	v_mul_f32_e32 v7, v89, v89
	v_mul_f32_e32 v60, v85, v85
	v_fmac_f32_e32 v7, v88, v88
	v_fmac_f32_e32 v60, v84, v84
	v_add_f32_e32 v7, v7, v60
	v_mul_f32_e32 v60, v87, v87
	v_mul_f32_e32 v61, v83, v83
	v_fmac_f32_e32 v60, v86, v86
	v_fmac_f32_e32 v61, v82, v82
	v_add_f32_e32 v60, v60, v61
	v_add_f32_e32 v7, v7, v60
	v_mul_f32_e32 v60, v73, v73
	v_mul_f32_e32 v61, v69, v69
	v_fmac_f32_e32 v60, v72, v72
	v_fmac_f32_e32 v61, v68, v68
	v_add_f32_e32 v60, v60, v61
	v_mul_f32_e32 v61, v71, v71
	v_mul_f32_e32 v62, v67, v67
	v_fmac_f32_e32 v61, v70, v70
	v_fmac_f32_e32 v62, v66, v66
	v_add_f32_e32 v61, v61, v62
	v_add_f32_e32 v60, v60, v61
	v_add_f32_e32 v7, v7, v60
	v_mov_b32_e32 v60, v7
	s_nop 1
	v_permlane16_swap_b32_e32 v7, v60
	v_add_f32_e32 v7, v7, v60
	v_mov_b32_e32 v60, v7
	s_nop 1
	v_permlane32_swap_b32_e32 v7, v60
	v_add_f32_e32 v7, v7, v60
	v_fmamk_f32 v7, v7, 0x3c800000, v217
	v_rsq_f32_e32 v7, v7
	v_pk_mul_f32 v[60:61], v[38:39], v[88:89]
	v_pk_mul_f32 v[62:63], v[40:41], v[84:85]
	v_pk_mul_f32 v[98:99], v[34:35], v[86:87]
	v_mul_f32_e32 v60, v60, v7
	v_mul_f32_e32 v61, v61, v7
	v_cvt_pk_bf16_f32 v60, v60, v61
	v_mul_f32_e32 v61, v62, v7
	v_mul_f32_e32 v62, v63, v7
	v_pk_mul_f32 v[64:65], v[36:37], v[82:83]
	v_cvt_pk_bf16_f32 v61, v61, v62
	v_mul_f32_e32 v62, v98, v7
	v_mul_f32_e32 v63, v99, v7
	v_cvt_pk_bf16_f32 v62, v62, v63
	v_mul_f32_e32 v63, v64, v7
	v_mul_f32_e32 v64, v65, v7
	v_cvt_pk_bf16_f32 v63, v63, v64
	global_store_dwordx4 v[58:59], v[60:63], off sc1
	v_pk_mul_f32 v[98:99], v[26:27], v[70:71]
	v_pk_mul_f32 v[64:65], v[28:29], v[66:67]
	v_pk_mul_f32 v[60:61], v[30:31], v[72:73]
	v_pk_mul_f32 v[62:63], v[32:33], v[68:69]
	v_mul_f32_e32 v60, v60, v7
	v_mul_f32_e32 v61, v61, v7
	v_cvt_pk_bf16_f32 v60, v60, v61
	v_mul_f32_e32 v61, v62, v7
	v_mul_f32_e32 v62, v63, v7
	v_cvt_pk_bf16_f32 v61, v61, v62
	v_mul_f32_e32 v62, v98, v7
	v_mul_f32_e32 v63, v99, v7
	v_cvt_pk_bf16_f32 v62, v62, v63
	v_mul_f32_e32 v63, v64, v7
	v_mul_f32_e32 v7, v65, v7
	v_cvt_pk_bf16_f32 v63, v63, v7
	global_store_dwordx4 v[58:59], v[60:63], off offset:64 sc1

.LBB0_1120:
	v_mov_b64_e32 v[58:59], v[74:75]
	v_mov_b64_e32 v[62:63], v[78:79]
	s_andn2_b64 vcc, exec, s[50:51]
	v_mov_b64_e32 v[60:61], v[76:77]
	v_mov_b64_e32 v[64:65], v[80:81]
	s_cbranch_vccnz .LBB0_1122
	v_ashrrev_i32_e32 v7, 31, v112
	v_lshrrev_b32_e32 v7, 19, v7
	v_add_u32_e32 v7, v112, v7
	v_and_b32_e32 v7, 0xffffe000, v7
	v_sub_u32_e32 v58, v112, v7
	v_ashrrev_i32_e32 v59, 31, v58
	v_lshlrev_b64 v[58:59], 7, v[58:59]
	v_lshl_add_u64 v[58:59], v[198:199], 0, v[58:59]
	global_load_dwordx4 v[62:65], v[58:59], off offset:16
	s_nop 0
	global_load_dwordx4 v[58:61], v[58:59], off
	v_mul_f32_e32 v7, v89, v89
	v_mul_f32_e32 v98, v85, v85
	v_fmac_f32_e32 v7, v88, v88
	v_fmac_f32_e32 v98, v84, v84
	v_add_f32_e32 v7, v7, v98
	v_mul_f32_e32 v98, v87, v87
	v_mul_f32_e32 v99, v83, v83
	v_fmac_f32_e32 v98, v86, v86
	v_fmac_f32_e32 v99, v82, v82
	v_add_f32_e32 v98, v98, v99
	v_add_f32_e32 v7, v7, v98
	v_mov_b32_e32 v98, v7
	s_nop 1
	v_permlane16_swap_b32_e32 v7, v98
	v_add_f32_e32 v7, v7, v98
	v_mov_b32_e32 v98, v7
	s_nop 1
	v_permlane32_swap_b32_e32 v7, v98
	v_add_f32_e32 v7, v7, v98
	v_fmamk_f32 v7, v7, 0x3d000000, v217
	v_rsq_f32_e32 v98, v7
	v_mov_b32_e32 v100, v88
	v_mov_b32_e32 v101, v86
	v_mov_b32_e32 v102, v38
	v_pk_mul_f32 v[100:101], v[100:101], v[98:99] op_sel_hi:[1,0]
	v_mov_b32_e32 v103, v34
	v_pk_mul_f32 v[100:101], v[102:103], v[100:101]
	s_nop 0
	v_pk_mul_f32 v[104:105], v[74:75], v[100:101]
	v_pk_mul_f32 v[100:101], v[74:75], v[100:101] op_sel:[1,0] op_sel_hi:[0,1]
	v_add_f32_e32 v99, v100, v101
	v_mov_b32_e32 v100, v89
	v_mov_b32_e32 v101, v87
	v_sub_f32_e32 v7, v104, v105
	v_pk_mul_f32 v[100:101], v[100:101], v[98:99] op_sel_hi:[1,0]
	v_mov_b32_e32 v104, v39
	v_mov_b32_e32 v105, v35
	v_pk_mul_f32 v[100:101], v[104:105], v[100:101]
	v_mul_f32_e32 v115, 0x3e16c740, v99
	v_pk_mul_f32 v[106:107], v[76:77], v[100:101]
	v_pk_mul_f32 v[100:101], v[76:77], v[100:101] op_sel:[1,0] op_sel_hi:[0,1]
	v_sub_f32_e32 v99, v106, v107
	v_mul_f32_e32 v116, 0x3e16c740, v99
	v_add_f32_e32 v99, v100, v101
	v_mov_b32_e32 v100, v84
	v_mov_b32_e32 v101, v82
	v_pk_mul_f32 v[100:101], v[100:101], v[98:99] op_sel_hi:[1,0]
	v_mov_b32_e32 v106, v40
	v_mov_b32_e32 v107, v36
	v_pk_mul_f32 v[100:101], v[106:107], v[100:101]
	v_mul_f32_e32 v117, 0x3e16c740, v99
	v_pk_mul_f32 v[108:109], v[78:79], v[100:101]
	v_pk_mul_f32 v[100:101], v[78:79], v[100:101] op_sel:[1,0] op_sel_hi:[0,1]
	v_sub_f32_e32 v99, v108, v109
	v_mul_f32_e32 v118, 0x3e16c740, v99
	v_add_f32_e32 v99, v100, v101
	v_mov_b32_e32 v100, v85
	v_mov_b32_e32 v101, v83
	v_mul_f32_e32 v119, 0x3e16c740, v99
	v_pk_mul_f32 v[98:99], v[100:101], v[98:99] op_sel_hi:[1,0]
	v_mov_b32_e32 v100, v41
	v_mov_b32_e32 v101, v37
	v_pk_mul_f32 v[98:99], v[100:101], v[98:99]
	v_mul_f32_e32 v7, 0x3e16c740, v7
	v_pk_mul_f32 v[108:109], v[80:81], v[98:99]
	v_pk_mul_f32 v[98:99], v[80:81], v[98:99] op_sel:[1,0] op_sel_hi:[0,1]
	v_add_f32_e32 v98, v98, v99
	v_mul_f32_e32 v120, 0x3e16c740, v98
	v_mov_b64_e32 v[98:99], s[28:29]
	v_sub_f32_e32 v108, v108, v109
	v_mad_i64_i32 v[98:99], s[0:1], v114, s70, v[98:99]
	v_mul_f32_e32 v109, 0x3e16c740, v108
	v_cvt_pk_bf16_f32 v108, v7, v116
	v_lshl_add_u64 v[98:99], v[8:9], 1, v[98:99]
	v_cvt_pk_bf16_f32 v109, v118, v109
	global_store_dwordx2 v[98:99], v[108:109], off offset:128 sc1
	v_cvt_pk_bf16_f32 v108, v115, v117
	v_mul_f32_e32 v7, v73, v73
	v_mul_f32_e32 v115, v69, v69
	v_fmac_f32_e32 v7, v72, v72
	v_fmac_f32_e32 v115, v68, v68
	v_add_f32_e32 v7, v7, v115
	v_mul_f32_e32 v115, v71, v71
	v_mul_f32_e32 v116, v67, v67
	v_fmac_f32_e32 v115, v70, v70
	v_fmac_f32_e32 v116, v66, v66
	v_add_f32_e32 v115, v115, v116
	v_add_f32_e32 v7, v7, v115
	v_mov_b32_e32 v115, v7
	s_nop 1
	v_permlane16_swap_b32_e32 v7, v115
	v_add_f32_e32 v7, v7, v115
	v_mov_b32_e32 v115, v7
	s_nop 1
	v_permlane32_swap_b32_e32 v7, v115
	v_add_f32_e32 v7, v7, v115
	v_fmamk_f32 v7, v7, 0x3d000000, v217
	v_rsq_f32_e32 v116, v7
	v_cvt_pk_bf16_f32 v109, v119, v120
	global_store_dwordx2 v[98:99], v[108:109], off offset:160 sc1
	v_mov_b32_e32 v108, v72
	v_mov_b32_e32 v109, v70
	v_pk_mul_f32 v[108:109], v[108:109], v[116:117] op_sel_hi:[1,0]
	s_nop 0
	v_pk_mul_f32 v[102:103], v[102:103], v[108:109]
	s_nop 0
	v_pk_mul_f32 v[108:109], v[74:75], v[102:103]
	v_pk_mul_f32 v[102:103], v[74:75], v[102:103] op_sel:[1,0] op_sel_hi:[0,1]
	v_add_f32_e32 v102, v102, v103
	v_sub_f32_e32 v7, v108, v109
	v_mul_f32_e32 v108, 0x3e16c740, v102
	v_mov_b32_e32 v102, v73
	v_mov_b32_e32 v103, v71
	v_pk_mul_f32 v[102:103], v[102:103], v[116:117] op_sel_hi:[1,0]
	v_mul_f32_e32 v7, 0x3e16c740, v7
	v_pk_mul_f32 v[102:103], v[104:105], v[102:103]
	s_nop 0
	v_pk_mul_f32 v[104:105], v[76:77], v[102:103]
	v_pk_mul_f32 v[102:103], v[76:77], v[102:103] op_sel:[1,0] op_sel_hi:[0,1]
	v_add_f32_e32 v102, v102, v103
	v_mul_f32_e32 v115, 0x3e16c740, v102
	v_mov_b32_e32 v102, v68
	v_mov_b32_e32 v103, v66
	v_pk_mul_f32 v[102:103], v[102:103], v[116:117] op_sel_hi:[1,0]
	v_sub_f32_e32 v104, v104, v105
	v_pk_mul_f32 v[102:103], v[106:107], v[102:103]
	v_mul_f32_e32 v109, 0x3e16c740, v104
	v_pk_mul_f32 v[104:105], v[78:79], v[102:103]
	v_pk_mul_f32 v[102:103], v[78:79], v[102:103] op_sel:[1,0] op_sel_hi:[0,1]
	v_add_f32_e32 v102, v102, v103
	v_sub_f32_e32 v104, v104, v105
	v_mul_f32_e32 v105, 0x3e16c740, v102
	v_mov_b32_e32 v102, v69
	v_mov_b32_e32 v103, v67
	v_pk_mul_f32 v[102:103], v[102:103], v[116:117] op_sel_hi:[1,0]
	v_mul_f32_e32 v104, 0x3e16c740, v104
	v_pk_mul_f32 v[100:101], v[100:101], v[102:103]
	s_nop 0
	v_pk_mul_f32 v[102:103], v[80:81], v[100:101]
	v_pk_mul_f32 v[100:101], v[80:81], v[100:101] op_sel:[1,0] op_sel_hi:[0,1]
	v_sub_f32_e32 v102, v102, v103
	v_add_f32_e32 v100, v100, v101
	v_mul_f32_e32 v102, 0x3e16c740, v102
	v_mul_f32_e32 v103, 0x3e16c740, v100
	v_cvt_pk_bf16_f32 v100, v7, v109
	v_cvt_pk_bf16_f32 v101, v104, v102
	global_store_dwordx2 v[98:99], v[100:101], off offset:320 sc1
	v_cvt_pk_bf16_f32 v100, v108, v115
	v_cvt_pk_bf16_f32 v101, v105, v103
	global_store_dwordx2 v[98:99], v[100:101], off offset:352 sc1

.Lew4_11:
	v_mul_f32_e32 v58, v85, v85
	v_fmac_f32_e32 v7, v88, v88
	v_fmac_f32_e32 v58, v84, v84
	v_add_f32_e32 v7, v7, v58
	v_mul_f32_e32 v58, v87, v87
	v_mul_f32_e32 v59, v83, v83
	v_fmac_f32_e32 v58, v86, v86
	v_fmac_f32_e32 v59, v82, v82
	v_add_f32_e32 v58, v58, v59
	v_add_f32_e32 v7, v7, v58
	v_mul_f32_e32 v58, v73, v73
	v_mul_f32_e32 v59, v69, v69
	v_fmac_f32_e32 v58, v72, v72
	v_fmac_f32_e32 v59, v68, v68
	v_add_f32_e32 v58, v58, v59
	v_mul_f32_e32 v59, v71, v71
	v_mul_f32_e32 v60, v67, v67
	v_fmac_f32_e32 v59, v70, v70
	v_fmac_f32_e32 v60, v66, v66
	v_add_f32_e32 v59, v59, v60
	v_add_f32_e32 v58, v58, v59
	v_add_f32_e32 v7, v7, v58
	v_mov_b32_e32 v58, v7
	s_nop 1
	v_permlane16_swap_b32_e32 v7, v58
	v_add_f32_e32 v7, v7, v58
	v_mov_b32_e32 v58, v7
	s_nop 1
	v_permlane32_swap_b32_e32 v7, v58
	v_add_f32_e32 v7, v7, v58
	v_fmamk_f32 v7, v7, 0x3c800000, v217
	v_rsq_f32_e32 v7, v7
	v_pk_mul_f32 v[58:59], v[38:39], v[88:89]
	v_pk_mul_f32 v[60:61], v[40:41], v[84:85]
	v_pk_mul_f32 v[64:65], v[36:37], v[82:83]
	v_mul_f32_e32 v7, 0x3e16c740, v7
	v_mul_f32_e32 v58, v58, v7
	v_mul_f32_e32 v59, v59, v7
	v_pk_mul_f32 v[82:83], v[34:35], v[86:87]
	v_cvt_pk_bf16_f32 v58, v58, v59
	v_mul_f32_e32 v59, v60, v7
	v_mul_f32_e32 v60, v61, v7
	v_cvt_pk_bf16_f32 v59, v59, v60
	v_mul_f32_e32 v60, v82, v7
	v_mul_f32_e32 v61, v83, v7
	v_mad_i64_i32 v[62:63], s[0:1], v114, s70, v[146:147]
	v_cvt_pk_bf16_f32 v60, v60, v61
	v_mul_f32_e32 v61, v64, v7
	v_mul_f32_e32 v64, v65, v7
	v_cvt_pk_bf16_f32 v61, v61, v64
	global_store_dwordx4 v[62:63], v[58:61], off sc1
	v_pk_mul_f32 v[64:65], v[28:29], v[66:67]
	v_pk_mul_f32 v[66:67], v[26:27], v[70:71]
	v_pk_mul_f32 v[58:59], v[30:31], v[72:73]
	v_pk_mul_f32 v[60:61], v[32:33], v[68:69]
	v_mul_f32_e32 v58, v58, v7
	v_mul_f32_e32 v59, v59, v7
	v_cvt_pk_bf16_f32 v58, v58, v59
	v_mul_f32_e32 v59, v60, v7
	v_mul_f32_e32 v60, v61, v7
	v_cvt_pk_bf16_f32 v59, v59, v60
	v_mul_f32_e32 v60, v66, v7
	v_mul_f32_e32 v61, v67, v7
	v_cvt_pk_bf16_f32 v60, v60, v61
	v_mul_f32_e32 v61, v64, v7
	v_mul_f32_e32 v7, v65, v7
	v_cvt_pk_bf16_f32 v61, v61, v7
	global_store_dwordx4 v[62:63], v[58:61], off offset:64 sc1
	v_mov_b64_e32 v[62:63], v[78:79]
	v_mov_b64_e32 v[64:65], v[80:81]
	v_mov_b64_e32 v[58:59], v[74:75]
	v_mov_b64_e32 v[60:61], v[76:77]

.Lew4_12:
	v_add_f32_e32 v7, v94, v95
	v_add_f32_e32 v66, v96, v97
	v_add_f32_e32 v7, v7, v66
	v_fmaak_f32 v7, v3, v7, 0x358637bd
	v_rsq_f32_e32 v74, v7
	s_and_b64 vcc, exec, s[8:9]
	s_mov_b64 s[50:51], -1
	v_pk_mul_f32 v[68:69], v[56:57], v[74:75] op_sel_hi:[1,0]
	v_pk_mul_f32 v[72:73], v[54:55], v[74:75] op_sel_hi:[1,0]
	v_pk_mul_f32 v[66:67], v[52:53], v[74:75] op_sel_hi:[1,0]
	v_pk_mul_f32 v[70:71], v[50:51], v[74:75] op_sel_hi:[1,0]
	v_pk_mul_f32 v[52:53], v[48:49], v[74:75] op_sel_hi:[1,0]
	v_pk_mul_f32 v[56:57], v[46:47], v[74:75] op_sel_hi:[1,0]
	v_pk_mul_f32 v[50:51], v[44:45], v[74:75] op_sel_hi:[1,0]
	v_pk_mul_f32 v[54:55], v[42:43], v[74:75] op_sel_hi:[1,0]
	s_cbranch_vccnz .LBB0_1135
	s_and_b64 vcc, exec, s[6:7]
	s_cbranch_vccnz .LBB0_1132
	v_lshlrev_b64 v[42:43], 11, v[112:113]
	v_lshl_add_u64 v[42:43], v[4:5], 0, v[42:43]
	s_andn2_b64 vcc, exec, s[26:27]
	s_cbranch_vccnz .LBB0_1129
	v_cvt_pk_bf16_f32 v44, v72, v73
	v_cvt_pk_bf16_f32 v45, v68, v69
	v_cvt_pk_bf16_f32 v46, v70, v71
	v_cvt_pk_bf16_f32 v47, v66, v67
	s_mov_b64 s[50:51], 0
	global_store_dwordx4 v[42:43], v[44:47], off sc1
	s_nop 1
	v_cvt_pk_bf16_f32 v44, v56, v57
	v_cvt_pk_bf16_f32 v45, v52, v53
	v_cvt_pk_bf16_f32 v46, v54, v55
	v_cvt_pk_bf16_f32 v47, v50, v51
	global_store_dwordx4 v[42:43], v[44:47], off offset:64 sc1
.LBB0_1129:
	s_andn2_b64 vcc, exec, s[50:51]
	s_cbranch_vccnz .LBB0_1131
	v_mul_f32_e32 v7, v73, v73
	v_mul_f32_e32 v44, v69, v69
	v_fmac_f32_e32 v7, v72, v72
	v_fmac_f32_e32 v44, v68, v68
	v_add_f32_e32 v7, v7, v44
	v_mul_f32_e32 v44, v71, v71
	v_mul_f32_e32 v45, v67, v67
	v_fmac_f32_e32 v44, v70, v70
	v_fmac_f32_e32 v45, v66, v66
	v_add_f32_e32 v44, v44, v45
	v_add_f32_e32 v7, v7, v44
	v_mul_f32_e32 v44, v57, v57
	v_mul_f32_e32 v45, v53, v53
	v_fmac_f32_e32 v44, v56, v56
	v_fmac_f32_e32 v45, v52, v52
	v_add_f32_e32 v44, v44, v45
	v_mul_f32_e32 v45, v55, v55
	v_mul_f32_e32 v46, v51, v51
	v_fmac_f32_e32 v45, v54, v54
	v_fmac_f32_e32 v46, v50, v50
	v_add_f32_e32 v45, v45, v46
	v_add_f32_e32 v44, v44, v45
	v_add_f32_e32 v7, v7, v44
	v_mov_b32_e32 v44, v7
	s_nop 1
	v_permlane16_swap_b32_e32 v7, v44
	v_add_f32_e32 v7, v7, v44
	v_mov_b32_e32 v44, v7
	s_nop 1
	v_permlane32_swap_b32_e32 v7, v44
	v_add_f32_e32 v7, v7, v44
	v_fmamk_f32 v7, v7, 0x3c800000, v217
	v_rsq_f32_e32 v7, v7
	v_pk_mul_f32 v[44:45], v[38:39], v[72:73]
	v_pk_mul_f32 v[46:47], v[40:41], v[68:69]
	v_pk_mul_f32 v[74:75], v[34:35], v[70:71]
	v_mul_f32_e32 v44, v44, v7
	v_mul_f32_e32 v45, v45, v7
	v_cvt_pk_bf16_f32 v44, v44, v45
	v_mul_f32_e32 v45, v46, v7
	v_mul_f32_e32 v46, v47, v7
	v_pk_mul_f32 v[48:49], v[36:37], v[66:67]
	v_cvt_pk_bf16_f32 v45, v45, v46
	v_mul_f32_e32 v46, v74, v7
	v_mul_f32_e32 v47, v75, v7
	v_cvt_pk_bf16_f32 v46, v46, v47
	v_mul_f32_e32 v47, v48, v7
	v_mul_f32_e32 v48, v49, v7
	v_cvt_pk_bf16_f32 v47, v47, v48
	global_store_dwordx4 v[42:43], v[44:47], off sc1
	v_pk_mul_f32 v[74:75], v[26:27], v[54:55]
	v_pk_mul_f32 v[48:49], v[28:29], v[50:51]
	v_pk_mul_f32 v[44:45], v[30:31], v[56:57]
	v_pk_mul_f32 v[46:47], v[32:33], v[52:53]
	v_mul_f32_e32 v44, v44, v7
	v_mul_f32_e32 v45, v45, v7
	v_cvt_pk_bf16_f32 v44, v44, v45
	v_mul_f32_e32 v45, v46, v7
	v_mul_f32_e32 v46, v47, v7
	v_cvt_pk_bf16_f32 v45, v45, v46
	v_mul_f32_e32 v46, v74, v7
	v_mul_f32_e32 v47, v75, v7
	v_cvt_pk_bf16_f32 v46, v46, v47
	v_mul_f32_e32 v47, v48, v7
	v_mul_f32_e32 v7, v49, v7
	v_cvt_pk_bf16_f32 v47, v47, v7
	global_store_dwordx4 v[42:43], v[44:47], off offset:64 sc1

.LBB0_1132:
	s_nop 0
	v_mov_b64_e32 v[46:47], v[58:59]
	v_mov_b64_e32 v[42:43], v[62:63]
	s_andn2_b64 vcc, exec, s[50:51]
	v_mov_b64_e32 v[48:49], v[60:61]
	v_mov_b64_e32 v[44:45], v[64:65]
	s_cbranch_vccnz .LBB0_1134
	v_ashrrev_i32_e32 v7, 31, v110
	v_lshrrev_b32_e32 v7, 19, v7
	v_add_u32_e32 v7, v110, v7
	v_and_b32_e32 v7, 0xffffe000, v7
	v_sub_u32_e32 v42, v110, v7
	v_ashrrev_i32_e32 v43, 31, v42
	v_lshlrev_b64 v[42:43], 7, v[42:43]
	v_lshl_add_u64 v[46:47], v[198:199], 0, v[42:43]
	global_load_dwordx4 v[42:45], v[46:47], off offset:16
	s_nop 0
	global_load_dwordx4 v[46:49], v[46:47], off
	v_mul_f32_e32 v7, v73, v73
	v_mul_f32_e32 v74, v69, v69
	v_fmac_f32_e32 v7, v72, v72
	v_fmac_f32_e32 v74, v68, v68
	v_add_f32_e32 v7, v7, v74
	v_mul_f32_e32 v74, v71, v71
	v_mul_f32_e32 v75, v67, v67
	v_fmac_f32_e32 v74, v70, v70
	v_fmac_f32_e32 v75, v66, v66
	v_add_f32_e32 v74, v74, v75
	v_add_f32_e32 v7, v7, v74
	v_mov_b32_e32 v74, v7
	s_nop 1
	v_permlane16_swap_b32_e32 v7, v74
	v_add_f32_e32 v7, v7, v74
	v_mov_b32_e32 v74, v7
	s_nop 1
	v_permlane32_swap_b32_e32 v7, v74
	v_add_f32_e32 v7, v7, v74
	v_fmamk_f32 v7, v7, 0x3d000000, v217
	v_rsq_f32_e32 v74, v7
	v_mov_b32_e32 v76, v72
	v_mov_b32_e32 v77, v70
	v_mov_b32_e32 v78, v38
	v_pk_mul_f32 v[76:77], v[76:77], v[74:75] op_sel_hi:[1,0]
	v_mov_b32_e32 v79, v34
	v_pk_mul_f32 v[76:77], v[78:79], v[76:77]
	s_nop 0
	v_pk_mul_f32 v[80:81], v[58:59], v[76:77]
	v_pk_mul_f32 v[76:77], v[58:59], v[76:77] op_sel:[1,0] op_sel_hi:[0,1]
	v_add_f32_e32 v75, v76, v77
	v_mov_b32_e32 v76, v73
	v_mov_b32_e32 v77, v71
	v_sub_f32_e32 v7, v80, v81
	v_pk_mul_f32 v[76:77], v[76:77], v[74:75] op_sel_hi:[1,0]
	v_mov_b32_e32 v80, v39
	v_mov_b32_e32 v81, v35
	v_pk_mul_f32 v[76:77], v[80:81], v[76:77]
	v_mul_f32_e32 v86, 0x3e16c740, v75
	v_pk_mul_f32 v[82:83], v[60:61], v[76:77]
	v_pk_mul_f32 v[76:77], v[60:61], v[76:77] op_sel:[1,0] op_sel_hi:[0,1]
	v_sub_f32_e32 v75, v82, v83
	v_mul_f32_e32 v87, 0x3e16c740, v75
	v_add_f32_e32 v75, v76, v77
	v_mov_b32_e32 v76, v68
	v_mov_b32_e32 v77, v66
	v_pk_mul_f32 v[76:77], v[76:77], v[74:75] op_sel_hi:[1,0]
	v_mov_b32_e32 v82, v40
	v_mov_b32_e32 v83, v36
	v_pk_mul_f32 v[76:77], v[82:83], v[76:77]
	v_mul_f32_e32 v88, 0x3e16c740, v75
	v_pk_mul_f32 v[84:85], v[62:63], v[76:77]
	v_pk_mul_f32 v[76:77], v[62:63], v[76:77] op_sel:[1,0] op_sel_hi:[0,1]
	v_sub_f32_e32 v75, v84, v85
	v_mul_f32_e32 v89, 0x3e16c740, v75
	v_add_f32_e32 v75, v76, v77
	v_mov_b32_e32 v76, v69
	v_mov_b32_e32 v77, v67
	v_mul_f32_e32 v94, 0x3e16c740, v75
	v_pk_mul_f32 v[74:75], v[76:77], v[74:75] op_sel_hi:[1,0]
	v_mov_b32_e32 v76, v41
	v_mov_b32_e32 v77, v37
	v_pk_mul_f32 v[74:75], v[76:77], v[74:75]
	v_mul_f32_e32 v7, 0x3e16c740, v7
	v_pk_mul_f32 v[84:85], v[64:65], v[74:75]
	v_pk_mul_f32 v[74:75], v[64:65], v[74:75] op_sel:[1,0] op_sel_hi:[0,1]
	v_add_f32_e32 v74, v74, v75
	v_mul_f32_e32 v95, 0x3e16c740, v74
	v_mov_b64_e32 v[74:75], s[28:29]
	v_sub_f32_e32 v84, v84, v85
	v_mad_i64_i32 v[74:75], s[0:1], v112, s70, v[74:75]
	v_mul_f32_e32 v85, 0x3e16c740, v84
	v_cvt_pk_bf16_f32 v84, v7, v87
	v_lshl_add_u64 v[74:75], v[8:9], 1, v[74:75]
	v_cvt_pk_bf16_f32 v85, v89, v85
	global_store_dwordx2 v[74:75], v[84:85], off offset:128 sc1
	v_cvt_pk_bf16_f32 v84, v86, v88
	v_mul_f32_e32 v7, v57, v57
	v_mul_f32_e32 v86, v53, v53
	v_fmac_f32_e32 v7, v56, v56
	v_fmac_f32_e32 v86, v52, v52
	v_add_f32_e32 v7, v7, v86
	v_mul_f32_e32 v86, v55, v55
	v_mul_f32_e32 v87, v51, v51
	v_fmac_f32_e32 v86, v54, v54
	v_fmac_f32_e32 v87, v50, v50
	v_add_f32_e32 v86, v86, v87
	v_add_f32_e32 v7, v7, v86
	v_mov_b32_e32 v86, v7
	s_nop 1
	v_permlane16_swap_b32_e32 v7, v86
	v_add_f32_e32 v7, v7, v86
	v_mov_b32_e32 v86, v7
	s_nop 1
	v_permlane32_swap_b32_e32 v7, v86
	v_add_f32_e32 v7, v7, v86
	v_fmamk_f32 v7, v7, 0x3d000000, v217
	v_rsq_f32_e32 v86, v7
	v_cvt_pk_bf16_f32 v85, v94, v95
	global_store_dwordx2 v[74:75], v[84:85], off offset:160 sc1
	v_mov_b32_e32 v84, v56
	v_mov_b32_e32 v85, v54
	v_pk_mul_f32 v[84:85], v[84:85], v[86:87] op_sel_hi:[1,0]
	s_nop 0
	v_pk_mul_f32 v[78:79], v[78:79], v[84:85]
	s_nop 0
	v_pk_mul_f32 v[84:85], v[58:59], v[78:79]
	v_pk_mul_f32 v[78:79], v[58:59], v[78:79] op_sel:[1,0] op_sel_hi:[0,1]
	v_add_f32_e32 v78, v78, v79
	v_sub_f32_e32 v7, v84, v85
	v_mul_f32_e32 v84, 0x3e16c740, v78
	v_mov_b32_e32 v78, v57
	v_mov_b32_e32 v79, v55
	v_pk_mul_f32 v[78:79], v[78:79], v[86:87] op_sel_hi:[1,0]
	v_mul_f32_e32 v7, 0x3e16c740, v7
	v_pk_mul_f32 v[78:79], v[80:81], v[78:79]
	s_nop 0
	v_pk_mul_f32 v[80:81], v[60:61], v[78:79]
	v_pk_mul_f32 v[78:79], v[60:61], v[78:79] op_sel:[1,0] op_sel_hi:[0,1]
	v_add_f32_e32 v78, v78, v79
	v_mul_f32_e32 v87, 0x3e16c740, v78
	v_mov_b32_e32 v78, v52
	v_mov_b32_e32 v79, v50
	v_pk_mul_f32 v[78:79], v[78:79], v[86:87] op_sel_hi:[1,0]
	v_sub_f32_e32 v80, v80, v81
	v_pk_mul_f32 v[78:79], v[82:83], v[78:79]
	v_mul_f32_e32 v85, 0x3e16c740, v80
	v_pk_mul_f32 v[80:81], v[62:63], v[78:79]
	v_pk_mul_f32 v[78:79], v[62:63], v[78:79] op_sel:[1,0] op_sel_hi:[0,1]
	v_add_f32_e32 v78, v78, v79
	v_sub_f32_e32 v80, v80, v81
	v_mul_f32_e32 v81, 0x3e16c740, v78
	v_mov_b32_e32 v78, v53
	v_mov_b32_e32 v79, v51
	v_pk_mul_f32 v[78:79], v[78:79], v[86:87] op_sel_hi:[1,0]
	v_mul_f32_e32 v80, 0x3e16c740, v80
	v_pk_mul_f32 v[76:77], v[76:77], v[78:79]
	s_nop 0
	v_pk_mul_f32 v[78:79], v[64:65], v[76:77]
	v_pk_mul_f32 v[76:77], v[64:65], v[76:77] op_sel:[1,0] op_sel_hi:[0,1]
	v_sub_f32_e32 v78, v78, v79
	v_add_f32_e32 v76, v76, v77
	v_mul_f32_e32 v78, 0x3e16c740, v78
	v_mul_f32_e32 v79, 0x3e16c740, v76
	v_cvt_pk_bf16_f32 v76, v7, v85
	v_cvt_pk_bf16_f32 v77, v80, v78
	global_store_dwordx2 v[74:75], v[76:77], off offset:320 sc1
	v_cvt_pk_bf16_f32 v76, v84, v87
	v_cvt_pk_bf16_f32 v77, v81, v79
	global_store_dwordx2 v[74:75], v[76:77], off offset:352 sc1

.Lew4_14:
	v_pk_mul_f32 v[48:49], v[36:37], v[66:67]
	v_mul_f32_e32 v7, 0x3e16c740, v7
	v_mul_f32_e32 v42, v42, v7
	v_mul_f32_e32 v43, v43, v7
	v_pk_mul_f32 v[66:67], v[34:35], v[70:71]
	v_cvt_pk_bf16_f32 v42, v42, v43
	v_mul_f32_e32 v43, v44, v7
	v_mul_f32_e32 v44, v45, v7
	v_cvt_pk_bf16_f32 v43, v43, v44
	v_mul_f32_e32 v44, v66, v7
	v_mul_f32_e32 v45, v67, v7
	v_mad_i64_i32 v[46:47], s[0:1], v112, s70, v[146:147]
	v_cvt_pk_bf16_f32 v44, v44, v45
	v_mul_f32_e32 v45, v48, v7
	v_mul_f32_e32 v48, v49, v7
	v_cvt_pk_bf16_f32 v45, v45, v48
	global_store_dwordx4 v[46:47], v[42:45], off sc1
	v_pk_mul_f32 v[48:49], v[28:29], v[50:51]
	v_pk_mul_f32 v[50:51], v[26:27], v[54:55]
	v_pk_mul_f32 v[42:43], v[30:31], v[56:57]
	v_pk_mul_f32 v[44:45], v[32:33], v[52:53]
	v_mul_f32_e32 v42, v42, v7
	v_mul_f32_e32 v43, v43, v7
	v_cvt_pk_bf16_f32 v42, v42, v43
	v_mul_f32_e32 v43, v44, v7
	v_mul_f32_e32 v44, v45, v7
	v_cvt_pk_bf16_f32 v43, v43, v44
	v_mul_f32_e32 v44, v50, v7
	v_mul_f32_e32 v45, v51, v7
	v_cvt_pk_bf16_f32 v44, v44, v45
	v_mul_f32_e32 v45, v48, v7
	v_mul_f32_e32 v7, v49, v7
	v_cvt_pk_bf16_f32 v45, v45, v7
	global_store_dwordx4 v[46:47], v[42:45], off offset:64 sc1
	v_mov_b64_e32 v[46:47], v[58:59]
	v_mov_b64_e32 v[48:49], v[60:61]
	v_mov_b64_e32 v[42:43], v[62:63]
	v_mov_b64_e32 v[44:45], v[64:65]

.LBB0_1140:
	s_and_b64 vcc, exec, s[6:7]
	s_mov_b64 s[6:7], -1
	s_cbranch_vccnz .LBB0_1146
	v_lshlrev_b64 v[50:51], 11, v[110:111]
	v_lshl_add_u64 v[4:5], v[4:5], 0, v[50:51]
	s_andn2_b64 vcc, exec, s[26:27]
	s_cbranch_vccnz .LBB0_1143
	v_cvt_pk_bf16_f32 v50, v22, v23
	v_cvt_pk_bf16_f32 v51, v24, v25
	v_cvt_pk_bf16_f32 v52, v18, v19
	v_cvt_pk_bf16_f32 v53, v20, v21
	s_mov_b64 s[6:7], 0
	global_store_dwordx4 v[4:5], v[50:53], off sc1
	s_nop 1
	v_cvt_pk_bf16_f32 v50, v14, v15
	v_cvt_pk_bf16_f32 v51, v16, v17
	v_cvt_pk_bf16_f32 v52, v10, v11
	v_cvt_pk_bf16_f32 v53, v12, v13
	global_store_dwordx4 v[4:5], v[50:53], off offset:64 sc1
.LBB0_1143:
	s_andn2_b64 vcc, exec, s[6:7]
	s_cbranch_vccnz .LBB0_1145
	v_mul_f32_e32 v3, v23, v23
	v_mul_f32_e32 v7, v25, v25
	v_fmac_f32_e32 v3, v22, v22
	v_fmac_f32_e32 v7, v24, v24
	v_add_f32_e32 v3, v3, v7
	v_mul_f32_e32 v7, v19, v19
	v_mul_f32_e32 v50, v21, v21
	v_fmac_f32_e32 v7, v18, v18
	v_fmac_f32_e32 v50, v20, v20
	v_add_f32_e32 v7, v7, v50
	v_add_f32_e32 v3, v3, v7
	v_mul_f32_e32 v7, v15, v15
	v_mul_f32_e32 v50, v17, v17
	v_fmac_f32_e32 v7, v14, v14
	v_fmac_f32_e32 v50, v16, v16
	v_add_f32_e32 v7, v7, v50
	v_mul_f32_e32 v50, v11, v11
	v_mul_f32_e32 v51, v13, v13
	v_fmac_f32_e32 v50, v10, v10
	v_fmac_f32_e32 v51, v12, v12
	v_add_f32_e32 v50, v50, v51
	v_add_f32_e32 v7, v7, v50
	v_add_f32_e32 v3, v3, v7
	v_mov_b32_e32 v7, v3
	s_nop 1
	v_permlane16_swap_b32_e32 v3, v7
	v_add_f32_e32 v3, v3, v7
	v_mov_b32_e32 v7, v3
	s_nop 1
	v_permlane32_swap_b32_e32 v3, v7
	v_add_f32_e32 v3, v3, v7
	v_fmamk_f32 v3, v3, 0x3c800000, v217
	v_rsq_f32_e32 v3, v3
	v_pk_mul_f32 v[50:51], v[38:39], v[22:23]
	v_pk_mul_f32 v[52:53], v[40:41], v[24:25]
	v_pk_mul_f32 v[54:55], v[36:37], v[20:21]
	v_mul_f32_e32 v7, v50, v3
	v_mul_f32_e32 v50, v51, v3
	v_pk_mul_f32 v[56:57], v[34:35], v[18:19]
	v_cvt_pk_bf16_f32 v50, v7, v50
	v_mul_f32_e32 v7, v52, v3
	v_mul_f32_e32 v51, v53, v3
	v_cvt_pk_bf16_f32 v51, v7, v51
	v_mul_f32_e32 v7, v56, v3
	v_mul_f32_e32 v52, v57, v3
	v_mul_f32_e32 v53, v55, v3
	v_cvt_pk_bf16_f32 v52, v7, v52
	v_mul_f32_e32 v7, v54, v3
	v_cvt_pk_bf16_f32 v53, v7, v53
	global_store_dwordx4 v[4:5], v[50:53], off sc1
	v_pk_mul_f32 v[56:57], v[26:27], v[10:11]
	v_pk_mul_f32 v[54:55], v[28:29], v[12:13]
	v_pk_mul_f32 v[50:51], v[30:31], v[14:15]
	v_pk_mul_f32 v[52:53], v[32:33], v[16:17]
	v_mul_f32_e32 v7, v50, v3
	v_mul_f32_e32 v50, v51, v3
	v_cvt_pk_bf16_f32 v50, v7, v50
	v_mul_f32_e32 v7, v52, v3
	v_mul_f32_e32 v51, v53, v3
	v_cvt_pk_bf16_f32 v51, v7, v51
	v_mul_f32_e32 v7, v56, v3
	v_mul_f32_e32 v52, v57, v3
	v_cvt_pk_bf16_f32 v52, v7, v52
	v_mul_f32_e32 v7, v54, v3
	v_mul_f32_e32 v3, v55, v3
	v_cvt_pk_bf16_f32 v53, v7, v3
	global_store_dwordx4 v[4:5], v[50:53], off offset:64 sc1

.LBB0_1146:
	s_andn2_b64 vcc, exec, s[6:7]
	s_cbranch_vccnz .LBB0_1148
	v_mul_f32_e32 v3, v23, v23
	v_mul_f32_e32 v4, v25, v25
	v_fmac_f32_e32 v3, v22, v22
	v_fmac_f32_e32 v4, v24, v24
	v_add_f32_e32 v3, v3, v4
	v_mul_f32_e32 v4, v19, v19
	v_mul_f32_e32 v5, v21, v21
	v_fmac_f32_e32 v4, v18, v18
	v_fmac_f32_e32 v5, v20, v20
	v_add_f32_e32 v4, v4, v5
	v_add_f32_e32 v3, v3, v4
	v_mov_b32_e32 v4, v3
	s_nop 1
	v_permlane16_swap_b32_e32 v3, v4
	v_add_f32_e32 v3, v3, v4
	v_mov_b32_e32 v4, v3
	s_nop 1
	v_permlane32_swap_b32_e32 v3, v4
	v_add_f32_e32 v3, v3, v4
	v_fmamk_f32 v3, v3, 0x3d000000, v217
	v_rsq_f32_e32 v4, v3
	v_mov_b32_e32 v50, v22
	v_mov_b32_e32 v51, v18
	v_mov_b32_e32 v52, v38
	v_pk_mul_f32 v[50:51], v[50:51], v[4:5] op_sel_hi:[1,0]
	v_mov_b32_e32 v53, v34
	v_pk_mul_f32 v[50:51], v[52:53], v[50:51]
	s_nop 0
	v_pk_mul_f32 v[54:55], v[46:47], v[50:51]
	v_pk_mul_f32 v[50:51], v[46:47], v[50:51] op_sel:[1,0] op_sel_hi:[0,1]
	v_add_f32_e32 v5, v50, v51
	v_mov_b32_e32 v50, v23
	v_mov_b32_e32 v51, v19
	v_sub_f32_e32 v3, v54, v55
	v_pk_mul_f32 v[50:51], v[50:51], v[4:5] op_sel_hi:[1,0]
	v_mov_b32_e32 v54, v39
	v_mov_b32_e32 v55, v35
	v_pk_mul_f32 v[50:51], v[54:55], v[50:51]
	v_mul_f32_e32 v7, 0x3e16c740, v5
	v_pk_mul_f32 v[56:57], v[48:49], v[50:51]
	v_pk_mul_f32 v[50:51], v[48:49], v[50:51] op_sel:[1,0] op_sel_hi:[0,1]
	v_sub_f32_e32 v5, v56, v57
	v_mul_f32_e32 v60, 0x3e16c740, v5
	v_add_f32_e32 v5, v50, v51
	v_mov_b32_e32 v50, v24
	v_mov_b32_e32 v51, v20
	v_pk_mul_f32 v[50:51], v[50:51], v[4:5] op_sel_hi:[1,0]
	v_mov_b32_e32 v56, v40
	v_mov_b32_e32 v57, v36
	v_pk_mul_f32 v[50:51], v[56:57], v[50:51]
	v_mul_f32_e32 v61, 0x3e16c740, v5
	v_pk_mul_f32 v[58:59], v[42:43], v[50:51]
	v_pk_mul_f32 v[50:51], v[42:43], v[50:51] op_sel:[1,0] op_sel_hi:[0,1]
	v_sub_f32_e32 v5, v58, v59
	v_mul_f32_e32 v62, 0x3e16c740, v5
	v_add_f32_e32 v5, v50, v51
	v_mov_b32_e32 v50, v25
	v_mov_b32_e32 v51, v21
	v_mul_f32_e32 v63, 0x3e16c740, v5
	v_pk_mul_f32 v[4:5], v[50:51], v[4:5] op_sel_hi:[1,0]
	v_mov_b32_e32 v50, v41
	v_mov_b32_e32 v51, v37
	v_pk_mul_f32 v[4:5], v[50:51], v[4:5]
	v_mul_f32_e32 v3, 0x3e16c740, v3
	v_pk_mul_f32 v[58:59], v[44:45], v[4:5]
	v_pk_mul_f32 v[4:5], v[44:45], v[4:5] op_sel:[1,0] op_sel_hi:[0,1]
	v_add_f32_e32 v4, v4, v5
	v_mul_f32_e32 v64, 0x3e16c740, v4
	v_mov_b64_e32 v[4:5], s[28:29]
	v_sub_f32_e32 v58, v58, v59
	v_mad_i64_i32 v[4:5], s[0:1], v110, s70, v[4:5]
	v_mul_f32_e32 v59, 0x3e16c740, v58
	v_lshl_add_u64 v[4:5], v[8:9], 1, v[4:5]
	v_cvt_pk_bf16_f32 v58, v3, v60
	v_cvt_pk_bf16_f32 v59, v62, v59
	global_store_dwordx2 v[4:5], v[58:59], off offset:128 sc1
	v_cvt_pk_bf16_f32 v8, v7, v61
	v_mul_f32_e32 v3, v15, v15
	v_mul_f32_e32 v7, v17, v17
	v_fmac_f32_e32 v3, v14, v14
	v_fmac_f32_e32 v7, v16, v16
	v_add_f32_e32 v3, v3, v7
	v_mul_f32_e32 v7, v11, v11
	v_mul_f32_e32 v58, v13, v13
	v_fmac_f32_e32 v7, v10, v10
	v_fmac_f32_e32 v58, v12, v12
	v_add_f32_e32 v7, v7, v58
	v_add_f32_e32 v3, v3, v7
	v_mov_b32_e32 v7, v3
	s_nop 1
	v_permlane16_swap_b32_e32 v3, v7
	v_add_f32_e32 v3, v3, v7
	v_mov_b32_e32 v7, v3
	s_nop 1
	v_permlane32_swap_b32_e32 v3, v7
	v_add_f32_e32 v3, v3, v7
	v_fmamk_f32 v3, v3, 0x3d000000, v217
	v_rsq_f32_e32 v58, v3
	v_cvt_pk_bf16_f32 v9, v63, v64
	global_store_dwordx2 v[4:5], v[8:9], off offset:160 sc1
	v_mov_b32_e32 v8, v14
	v_mov_b32_e32 v9, v10
	v_pk_mul_f32 v[8:9], v[8:9], v[58:59] op_sel_hi:[1,0]
	s_nop 0
	v_pk_mul_f32 v[8:9], v[52:53], v[8:9]
	s_nop 0
	v_pk_mul_f32 v[52:53], v[46:47], v[8:9]
	v_pk_mul_f32 v[8:9], v[46:47], v[8:9] op_sel:[1,0] op_sel_hi:[0,1]
	v_add_f32_e32 v7, v8, v9
	v_mov_b32_e32 v8, v15
	v_mov_b32_e32 v9, v11
	v_pk_mul_f32 v[8:9], v[8:9], v[58:59] op_sel_hi:[1,0]
	v_sub_f32_e32 v3, v52, v53
	v_pk_mul_f32 v[8:9], v[54:55], v[8:9]
	v_mul_f32_e32 v3, 0x3e16c740, v3
	v_pk_mul_f32 v[46:47], v[48:49], v[8:9]
	v_pk_mul_f32 v[8:9], v[48:49], v[8:9] op_sel:[1,0] op_sel_hi:[0,1]
	v_add_f32_e32 v8, v8, v9
	v_mul_f32_e32 v48, 0x3e16c740, v8
	v_mov_b32_e32 v8, v16
	v_mov_b32_e32 v9, v12
	v_pk_mul_f32 v[8:9], v[8:9], v[58:59] op_sel_hi:[1,0]
	v_sub_f32_e32 v46, v46, v47
	v_pk_mul_f32 v[8:9], v[56:57], v[8:9]
	v_mul_f32_e32 v52, 0x3e16c740, v46
	v_pk_mul_f32 v[46:47], v[42:43], v[8:9]
	v_pk_mul_f32 v[8:9], v[42:43], v[8:9] op_sel:[1,0] op_sel_hi:[0,1]
	v_add_f32_e32 v8, v8, v9
	v_sub_f32_e32 v46, v46, v47
	v_mul_f32_e32 v47, 0x3e16c740, v8
	v_mov_b32_e32 v8, v17
	v_mov_b32_e32 v9, v13
	v_pk_mul_f32 v[8:9], v[8:9], v[58:59] op_sel_hi:[1,0]
	v_mul_f32_e32 v46, 0x3e16c740, v46
	v_pk_mul_f32 v[8:9], v[50:51], v[8:9]
	v_mul_f32_e32 v7, 0x3e16c740, v7
	v_pk_mul_f32 v[42:43], v[44:45], v[8:9]
	v_pk_mul_f32 v[8:9], v[44:45], v[8:9] op_sel:[1,0] op_sel_hi:[0,1]
	v_sub_f32_e32 v42, v42, v43
	v_add_f32_e32 v8, v8, v9
	v_mul_f32_e32 v42, 0x3e16c740, v42
	v_mul_f32_e32 v43, 0x3e16c740, v8
	v_cvt_pk_bf16_f32 v8, v3, v52
	v_cvt_pk_bf16_f32 v9, v46, v42
	global_store_dwordx2 v[4:5], v[8:9], off offset:320 sc1
	v_cvt_pk_bf16_f32 v8, v7, v48
	v_cvt_pk_bf16_f32 v9, v47, v43
	global_store_dwordx2 v[4:5], v[8:9], off offset:352 sc1

.LBB0_1149:
	v_mul_f32_e32 v3, v23, v23
	v_mul_f32_e32 v4, v25, v25
	v_fmac_f32_e32 v3, v22, v22
	v_fmac_f32_e32 v4, v24, v24
	v_add_f32_e32 v3, v3, v4
	v_mul_f32_e32 v4, v19, v19
	v_mul_f32_e32 v5, v21, v21
	v_fmac_f32_e32 v4, v18, v18
	v_fmac_f32_e32 v5, v20, v20
	v_add_f32_e32 v4, v4, v5
	v_add_f32_e32 v3, v3, v4
	v_mul_f32_e32 v4, v15, v15
	v_mul_f32_e32 v5, v17, v17
	v_fmac_f32_e32 v4, v14, v14
	v_fmac_f32_e32 v5, v16, v16
	v_add_f32_e32 v4, v4, v5
	v_mul_f32_e32 v5, v11, v11
	v_mul_f32_e32 v7, v13, v13
	v_fmac_f32_e32 v5, v10, v10
	v_fmac_f32_e32 v7, v12, v12
	v_add_f32_e32 v5, v5, v7
	v_add_f32_e32 v4, v4, v5
	v_add_f32_e32 v3, v3, v4
	v_mov_b32_e32 v4, v3
	s_nop 1
	v_permlane16_swap_b32_e32 v3, v4
	v_add_f32_e32 v3, v3, v4
	v_mov_b32_e32 v4, v3
	s_nop 1
	v_permlane32_swap_b32_e32 v3, v4
	v_add_f32_e32 v3, v3, v4
	v_fmamk_f32 v3, v3, 0x3c800000, v217
	v_rsq_f32_e32 v3, v3
	v_pk_mul_f32 v[22:23], v[38:39], v[22:23]
	v_pk_mul_f32 v[8:9], v[40:41], v[24:25]
	v_pk_mul_f32 v[24:25], v[36:37], v[20:21]
	v_mul_f32_e32 v3, 0x3e16c740, v3
	v_pk_mul_f32 v[20:21], v[34:35], v[18:19]
	v_mul_f32_e32 v7, v22, v3
	v_mul_f32_e32 v18, v23, v3
	v_cvt_pk_bf16_f32 v18, v7, v18
	v_mul_f32_e32 v7, v8, v3
	v_mul_f32_e32 v8, v9, v3
	v_cvt_pk_bf16_f32 v19, v7, v8
	v_mul_f32_e32 v8, v21, v3
	v_mul_f32_e32 v7, v20, v3
	v_cvt_pk_bf16_f32 v20, v7, v8
	v_mul_f32_e32 v8, v25, v3
	v_mul_f32_e32 v7, v24, v3
	v_cvt_pk_bf16_f32 v21, v7, v8
	v_pk_mul_f32 v[8:9], v[30:31], v[14:15]
	v_mad_i64_i32 v[4:5], s[0:1], v110, s70, v[146:147]
	v_pk_mul_f32 v[16:17], v[32:33], v[16:17]
	v_mul_f32_e32 v7, v8, v3
	v_mul_f32_e32 v8, v9, v3
	global_store_dwordx4 v[4:5], v[18:21], off sc1
	v_pk_mul_f32 v[10:11], v[26:27], v[10:11]
	v_cvt_pk_bf16_f32 v8, v7, v8
	v_mul_f32_e32 v7, v16, v3
	v_mul_f32_e32 v9, v17, v3
	v_pk_mul_f32 v[12:13], v[28:29], v[12:13]
	v_cvt_pk_bf16_f32 v9, v7, v9
	v_mul_f32_e32 v7, v10, v3
	v_mul_f32_e32 v10, v11, v3
	v_cvt_pk_bf16_f32 v10, v7, v10
	v_mul_f32_e32 v7, v12, v3
	v_mul_f32_e32 v3, v13, v3
	v_cvt_pk_bf16_f32 v11, v7, v3
	global_store_dwordx4 v[4:5], v[8:11], off offset:64 sc1
	s_and_b64 vcc, exec, s[4:5]
	s_mov_b64 s[4:5], -1
	s_cbranch_vccnz .LBB0_1032
